# plus GEMM K-loop heads aligned to 64 B and the mid-phase setprio 0/1 flip pairs removed
# speedup vs baseline: 1.0104x; 1.0104x over previous
;     __device__ bool next(int i, Unit& u) const { const int j = first + i * G; if (j >= count) return false; u.pm = j / nN; u.pn = j % nN; return true; }
; #define PG8_STAGE(bufoff, gbase, voff) do { _Pragma("unroll") for (int _i = 0; _i < 2; ++_i) \
;         __builtin_amdgcn_global_load_lds((const unsigned*)((const char*)(gbase) + (voff)[_i]), (PG8_LAS unsigned*)(lds + (bufoff) + ldsw + _i * 8192), 16, 0, 0); } while (0)
; #define PG8_LDA(dst, b, h) do { _Pragma("unroll") for (int m = 0; m < 4; ++m) _Pragma("unroll") for (int k = 0; k < 2; ++k) dst[m][k] = *(const PG8_LAS bf16x8*)(lds + PG8_SA(b, h) + aoff + m * 2048 + k * 1024); } while (0)
; #define PG8_LDB(dst, b, h) do { _Pragma("unroll") for (int n = 0; n < 2; ++n) _Pragma("unroll") for (int k = 0; k < 2; ++k) dst[n][k] = *(const PG8_LAS bf16x8*)(lds + PG8_SB(b, h) + boff + n * 2048 + k * 1024); } while (0)
; #define PG8_SCHED __builtin_amdgcn_sched_barrier(0)
; template <class Epi, class Sched, bool ALIGN_EPI = false, bool SP2 = false>
; __device__ __forceinline__ void gemm_phase(PG8_LAS unsigned char* lds, const Gemm g, const Sched& S, const Epi& E) {
;     ...
;         const bool has_next = S.next(ui + 1, nxt);
;         const char* nA = has_next ? (const char*)g.A + (size_t)nxt.pm * tstep : cA; const char* nB = has_next ? (const char*)g.Bt + (size_t)nxt.pn * tstep : cB;
;         for (int t = 0; t < nt; t += 2) {
;             const bool last = (t == nt - 2);
;             const char* a1 = cA + (size_t)(t + 1) * kstep;
;             const char* a2 = last ? nA : cA + (size_t)(t + 2) * kstep; const char* b2 = last ? nB : cB + (size_t)(t + 2) * kstep;
;             const char* a3 = a2 + kstep; const char* b3 = b2 + kstep;
;             if (last && has_next) S.a_ready(nxt);
;             if constexpr (SP2) {
;             PG8_LDB(B0, 0, 0); PG8_LDB(B1, 0, 1); PG8_SCHED; PG8_LDA(At, 0, 0); PG8_STAGE(PG8_SA(1, 1), a1 + hstep, voffA);
;     ...
; #pragma unroll
;         for (int a = 0; a < 2; ++a)
; #pragma unroll
;             for (int b = 0; b < 2; ++b)
; #pragma unroll
;                 for (int m = 0; m < 4; ++m)
; #pragma unroll
;                     for (int n = 0; n < 2; ++n) acc[a][b][m][n] = (f32x4){0.f, 0.f, 0.f, 0.f};
.LBB0_114:
	s_ashr_i32 s21, s20, 31
	s_lshl_b64 s[8:9], s[20:21], 20
	v_readlane_b32 s22, v254, 16
	v_readlane_b32 s23, v254, 17
	s_add_u32 s22, s22, s8
	s_addc_u32 s23, s23, s9
	s_and_b64 s[8:9], s[2:3], exec
	s_cselect_b32 s21, s23, s5
	s_cselect_b32 s26, s22, s4
	s_ashr_i32 s19, s18, 31
	s_lshl_b64 s[8:9], s[18:19], 20
	s_add_u32 s24, s30, s8
	s_addc_u32 s25, s31, s9
	s_and_b64 s[8:9], s[2:3], exec
	s_cselect_b32 s19, s25, s7
	s_cselect_b32 s27, s24, s6
	s_add_u32 s4, s4, 0x80080
	s_addc_u32 s5, s5, 0
	s_add_u32 s28, s6, 0x100
	v_mov_b32_e32 v2, 0
	s_addc_u32 s29, s7, 0
	s_mov_b32 s52, -2
	v_mov_b32_e32 v3, v2
	v_mov_b32_e32 v4, v2
	v_mov_b32_e32 v5, v2
	v_mov_b32_e32 v6, v2
	v_mov_b32_e32 v7, v2
	v_mov_b32_e32 v8, v2
	v_mov_b32_e32 v9, v2
	v_mov_b32_e32 v10, v2
	v_mov_b32_e32 v11, v2
	v_mov_b32_e32 v12, v2
	v_mov_b32_e32 v13, v2
	v_mov_b32_e32 v18, v2
	v_mov_b32_e32 v19, v2
	v_mov_b32_e32 v20, v2
	v_mov_b32_e32 v21, v2
	v_mov_b32_e32 v26, v2
	v_mov_b32_e32 v27, v2
	v_mov_b32_e32 v28, v2
	v_mov_b32_e32 v29, v2
	v_mov_b32_e32 v34, v2
	v_mov_b32_e32 v35, v2
	v_mov_b32_e32 v36, v2
	v_mov_b32_e32 v37, v2
	v_mov_b32_e32 v42, v2
	v_mov_b32_e32 v43, v2
	v_mov_b32_e32 v44, v2
	v_mov_b32_e32 v45, v2
	v_mov_b32_e32 v50, v2
	v_mov_b32_e32 v51, v2
	v_mov_b32_e32 v52, v2
	v_mov_b32_e32 v53, v2
	v_mov_b32_e32 v14, v2
	v_mov_b32_e32 v15, v2
	v_mov_b32_e32 v16, v2
	v_mov_b32_e32 v17, v2
	v_mov_b32_e32 v22, v2
	v_mov_b32_e32 v23, v2
	v_mov_b32_e32 v24, v2
	v_mov_b32_e32 v25, v2
	v_mov_b32_e32 v30, v2
	v_mov_b32_e32 v31, v2
	v_mov_b32_e32 v32, v2
	v_mov_b32_e32 v33, v2
	v_mov_b32_e32 v38, v2
	v_mov_b32_e32 v39, v2
	v_mov_b32_e32 v40, v2
	v_mov_b32_e32 v41, v2
	v_mov_b32_e32 v46, v2
	v_mov_b32_e32 v47, v2
	v_mov_b32_e32 v48, v2
	v_mov_b32_e32 v49, v2
	v_mov_b32_e32 v54, v2
	v_mov_b32_e32 v55, v2
	v_mov_b32_e32 v56, v2
	v_mov_b32_e32 v57, v2
	v_mov_b32_e32 v58, v2
	v_mov_b32_e32 v59, v2
	v_mov_b32_e32 v60, v2
	v_mov_b32_e32 v61, v2
	v_mov_b32_e32 v62, v2
	v_mov_b32_e32 v63, v2
	v_mov_b32_e32 v64, v2
	v_mov_b32_e32 v65, v2
	v_mov_b32_e32 v66, v2
	v_mov_b32_e32 v67, v2
	v_mov_b32_e32 v68, v2
	v_mov_b32_e32 v69, v2
	v_mov_b32_e32 v70, v2
	v_mov_b32_e32 v71, v2
	v_mov_b32_e32 v72, v2
	v_mov_b32_e32 v73, v2
	v_mov_b32_e32 v74, v2
	v_mov_b32_e32 v75, v2
	v_mov_b32_e32 v76, v2
	v_mov_b32_e32 v77, v2
	v_mov_b32_e32 v82, v2
	v_mov_b32_e32 v83, v2
	v_mov_b32_e32 v84, v2
	v_mov_b32_e32 v85, v2
	v_mov_b32_e32 v90, v2
	v_mov_b32_e32 v91, v2
	v_mov_b32_e32 v92, v2
	v_mov_b32_e32 v93, v2
	v_mov_b32_e32 v98, v2
	v_mov_b32_e32 v99, v2
	v_mov_b32_e32 v100, v2
	v_mov_b32_e32 v101, v2
	v_mov_b32_e32 v106, v2
	v_mov_b32_e32 v107, v2
	v_mov_b32_e32 v108, v2
	v_mov_b32_e32 v109, v2
	v_mov_b32_e32 v114, v2
	v_mov_b32_e32 v115, v2
	v_mov_b32_e32 v116, v2
	v_mov_b32_e32 v117, v2
	v_mov_b32_e32 v78, v2
	v_mov_b32_e32 v79, v2
	v_mov_b32_e32 v80, v2
	v_mov_b32_e32 v81, v2
	v_mov_b32_e32 v86, v2
	v_mov_b32_e32 v87, v2
	v_mov_b32_e32 v88, v2
	v_mov_b32_e32 v89, v2
	v_mov_b32_e32 v94, v2
	v_mov_b32_e32 v95, v2
	v_mov_b32_e32 v96, v2
	v_mov_b32_e32 v97, v2
	v_mov_b32_e32 v102, v2
	v_mov_b32_e32 v103, v2
	v_mov_b32_e32 v104, v2
	v_mov_b32_e32 v105, v2
	v_mov_b32_e32 v110, v2
	v_mov_b32_e32 v111, v2
	v_mov_b32_e32 v112, v2
	v_mov_b32_e32 v113, v2
	v_mov_b32_e32 v118, v2
	v_mov_b32_e32 v119, v2
	v_mov_b32_e32 v120, v2
	v_mov_b32_e32 v121, v2
	v_mov_b32_e32 v122, v2
	v_mov_b32_e32 v123, v2
	v_mov_b32_e32 v124, v2
	v_mov_b32_e32 v125, v2
	v_mov_b32_e32 v126, v2
	v_mov_b32_e32 v127, v2
	v_mov_b32_e32 v128, v2
	v_mov_b32_e32 v129, v2
	.p2align 6
.LBB0_115:
	s_add_u32 s6, s4, 0xfff80080
	s_addc_u32 s7, s5, -1
	s_add_i32 s53, 0, 0x10000
	s_cmp_eq_u32 s52, 28
	s_cselect_b32 s9, s21, s7
	s_cselect_b32 s8, s26, s6
	s_cselect_b32 s7, s19, s29
	s_cselect_b32 s6, s27, s28
	s_add_i32 s56, 0, 0x14000
	v_add_u32_e32 v142, s53, v162
	v_add_u32_e32 v156, s56, v162
	ds_read_b128 v[130:133], v142
	ds_read_b128 v[134:137], v142 offset:1024
	ds_read_b128 v[138:141], v142 offset:2048
	ds_read_b128 v[142:145], v142 offset:3072
	ds_read_b128 v[178:181], v156
	ds_read_b128 v[182:185], v156 offset:1024
	ds_read_b128 v[200:203], v156 offset:2048
	ds_read_b128 v[204:207], v156 offset:3072
	v_lshl_add_u64 v[156:157], s[4:5], 0, v[152:153]
	s_add_i32 m0, s34, 0xc000
	ds_read_b128 v[208:211], v176
	ds_read_b128 v[212:215], v176 offset:1024
	ds_read_b128 v[216:219], v176 offset:2048
	ds_read_b128 v[220:223], v176 offset:3072
	ds_read_b128 v[224:227], v176 offset:4096
	ds_read_b128 v[228:231], v176 offset:5120
	ds_read_b128 v[232:235], v176 offset:6144
	ds_read_b128 v[236:239], v176 offset:7168
	global_load_lds_dwordx4 v[156:157], off
	v_lshl_add_u64 v[156:157], s[4:5], 0, v[154:155]
	s_add_i32 m0, s34, 0xe000
	s_nop 0
	global_load_lds_dwordx4 v[156:157], off
	s_waitcnt vmcnt(8)
	s_waitcnt lgkmcnt(0)
	s_barrier
; #define PG8_STAGE(bufoff, gbase, voff) do { _Pragma("unroll") for (int _i = 0; _i < 2; ++_i) \
;         __builtin_amdgcn_global_load_lds((const unsigned*)((const char*)(gbase) + (voff)[_i]), (PG8_LAS unsigned*)(lds + (bufoff) + ldsw + _i * 8192), 16, 0, 0); } while (0)
; #define PG8_LDA(dst, b, h) do { _Pragma("unroll") for (int m = 0; m < 4; ++m) _Pragma("unroll") for (int k = 0; k < 2; ++k) dst[m][k] = *(const PG8_LAS bf16x8*)(lds + PG8_SA(b, h) + aoff + m * 2048 + k * 1024); } while (0)
; #define PG8_MMA(ai, bj, At, Bt) do { __builtin_amdgcn_s_setprio(1); _Pragma("unroll") for (int m = 0; m < 4; ++m) _Pragma("unroll") for (int n = 0; n < 2; ++n) _Pragma("unroll") for (int k = 0; k < 2; ++k) \
;         acc[ai][bj][m][n] = __builtin_amdgcn_mfma_f32_16x16x32_bf16(Bt[n][k], At[m][k], acc[ai][bj][m][n], 0, 0, 0); __builtin_amdgcn_s_setprio(0); } while (0)
; #define PG8_WAIT_V(n) asm volatile("s_waitcnt vmcnt(" #n ")" ::: "memory")
; #define PG8_WAIT_L(n) asm volatile("s_waitcnt lgkmcnt(" #n ")" ::: "memory")
; #define PG8_BAR __builtin_amdgcn_s_barrier()
; #define PG8_SCHED __builtin_amdgcn_sched_barrier(0)
; template <class Epi, class Sched, bool ALIGN_EPI = false, bool SP2 = false>
; __device__ __forceinline__ void gemm_phase(PG8_LAS unsigned char* lds, const Gemm g, const Sched& S, const Epi& E) {
;     ...
;             PG8_WAIT_V(8); PG8_WAIT_L(0); PG8_BAR; PG8_MMA(0, 0, At, B0); PG8_MMA(0, 1, At, B1); PG8_BAR; PG8_SCHED;
;             PG8_LDA(At, 0, 1); PG8_STAGE(PG8_SB(0, 0), b2, voffB); PG8_STAGE(PG8_SB(0, 1), b2 + hstep, voffB); PG8_STAGE(PG8_SA(0, 0), a2, voffA);
;             PG8_WAIT_V(8); PG8_WAIT_L(0); PG8_BAR; PG8_MMA(1, 0, At, B0); PG8_MMA(1, 1, At, B1); PG8_BAR; PG8_SCHED;
	s_setprio 1
	s_waitcnt lgkmcnt(0)
	v_mfma_f32_16x16x32_bf16 v[126:129], v[130:133], v[208:211], v[126:129]
	v_mfma_f32_16x16x32_bf16 v[122:125], v[138:141], v[208:211], v[122:125]
	v_mfma_f32_16x16x32_bf16 v[118:121], v[130:133], v[216:219], v[118:121]
	v_mfma_f32_16x16x32_bf16 v[110:113], v[138:141], v[216:219], v[110:113]
	v_mfma_f32_16x16x32_bf16 v[102:105], v[130:133], v[224:227], v[102:105]
	v_mfma_f32_16x16x32_bf16 v[94:97], v[138:141], v[224:227], v[94:97]
	v_mfma_f32_16x16x32_bf16 v[86:89], v[130:133], v[232:235], v[86:89]
	v_mfma_f32_16x16x32_bf16 v[78:81], v[138:141], v[232:235], v[78:81]
	v_mfma_f32_16x16x32_bf16 v[126:129], v[134:137], v[212:215], v[126:129]
	v_mfma_f32_16x16x32_bf16 v[122:125], v[142:145], v[212:215], v[122:125]
	v_mfma_f32_16x16x32_bf16 v[118:121], v[134:137], v[220:223], v[118:121]
	v_mfma_f32_16x16x32_bf16 v[110:113], v[142:145], v[220:223], v[110:113]
	v_mfma_f32_16x16x32_bf16 v[102:105], v[134:137], v[228:231], v[102:105]
	v_mfma_f32_16x16x32_bf16 v[94:97], v[142:145], v[228:231], v[94:97]
	v_mfma_f32_16x16x32_bf16 v[86:89], v[134:137], v[236:239], v[86:89]
	v_mfma_f32_16x16x32_bf16 v[78:81], v[142:145], v[236:239], v[78:81]
	v_mfma_f32_16x16x32_bf16 v[114:117], v[178:181], v[208:211], v[114:117]
	v_mfma_f32_16x16x32_bf16 v[106:109], v[200:203], v[208:211], v[106:109]
	v_mfma_f32_16x16x32_bf16 v[98:101], v[178:181], v[216:219], v[98:101]
	v_mfma_f32_16x16x32_bf16 v[90:93], v[200:203], v[216:219], v[90:93]
	v_mfma_f32_16x16x32_bf16 v[82:85], v[178:181], v[224:227], v[82:85]
	v_mfma_f32_16x16x32_bf16 v[74:77], v[200:203], v[224:227], v[74:77]
	v_mfma_f32_16x16x32_bf16 v[70:73], v[178:181], v[232:235], v[70:73]
	v_mfma_f32_16x16x32_bf16 v[66:69], v[200:203], v[232:235], v[66:69]
	v_mfma_f32_16x16x32_bf16 v[114:117], v[182:185], v[212:215], v[114:117]
	v_mfma_f32_16x16x32_bf16 v[106:109], v[204:207], v[212:215], v[106:109]
	v_mfma_f32_16x16x32_bf16 v[98:101], v[182:185], v[220:223], v[98:101]
	v_mfma_f32_16x16x32_bf16 v[90:93], v[204:207], v[220:223], v[90:93]
	v_mfma_f32_16x16x32_bf16 v[82:85], v[182:185], v[228:231], v[82:85]
	v_mfma_f32_16x16x32_bf16 v[74:77], v[204:207], v[228:231], v[74:77]
	v_mfma_f32_16x16x32_bf16 v[70:73], v[182:185], v[236:239], v[70:73]
	v_mfma_f32_16x16x32_bf16 v[66:69], v[204:207], v[236:239], v[66:69]
	s_setprio 0
	s_barrier
	s_add_i32 s53, s53, s33
	v_lshl_add_u64 v[156:157], s[6:7], 0, v[0:1]
	s_mov_b32 m0, s53
	ds_read_b128 v[208:211], v176 offset:16384
	ds_read_b128 v[212:215], v176 offset:17408
	ds_read_b128 v[216:219], v176 offset:18432
	ds_read_b128 v[220:223], v176 offset:19456
	ds_read_b128 v[224:227], v176 offset:20480
	ds_read_b128 v[228:231], v176 offset:21504
	ds_read_b128 v[232:235], v176 offset:22528
	ds_read_b128 v[236:239], v176 offset:23552
	global_load_lds_dwordx4 v[156:157], off
	s_add_i32 m0, s53, 0x2000
	s_add_u32 s54, s6, 0x80000
	v_lshl_add_u64 v[164:165], s[6:7], 0, v[146:147]
	s_addc_u32 s55, s7, 0
	s_add_i32 s53, s56, s33
	global_load_lds_dwordx4 v[164:165], off
	v_lshl_add_u64 v[166:167], s[54:55], 0, v[0:1]
	s_mov_b32 m0, s53
	v_lshl_add_u64 v[172:173], s[8:9], 0, v[148:149]
	global_load_lds_dwordx4 v[166:167], off
	v_lshl_add_u64 v[166:167], s[54:55], 0, v[146:147]
	s_add_i32 m0, s53, 0x2000
	s_nop 0
	global_load_lds_dwordx4 v[166:167], off
	v_lshl_add_u64 v[166:167], s[8:9], 0, v[150:151]
	s_mov_b32 m0, s34
	s_nop 0
	global_load_lds_dwordx4 v[166:167], off
	s_mov_b32 m0, s35
	s_nop 0
	global_load_lds_dwordx4 v[172:173], off
	s_waitcnt vmcnt(8)
	s_waitcnt lgkmcnt(0)
	s_barrier
	s_setprio 1
	s_waitcnt lgkmcnt(0)
	v_mfma_f32_16x16x32_bf16 v[62:65], v[130:133], v[208:211], v[62:65]
	v_mfma_f32_16x16x32_bf16 v[58:61], v[138:141], v[208:211], v[58:61]
	v_mfma_f32_16x16x32_bf16 v[54:57], v[130:133], v[216:219], v[54:57]
	v_mfma_f32_16x16x32_bf16 v[46:49], v[138:141], v[216:219], v[46:49]
	v_mfma_f32_16x16x32_bf16 v[38:41], v[130:133], v[224:227], v[38:41]
	v_mfma_f32_16x16x32_bf16 v[30:33], v[138:141], v[224:227], v[30:33]
	v_mfma_f32_16x16x32_bf16 v[22:25], v[130:133], v[232:235], v[22:25]
	v_mfma_f32_16x16x32_bf16 v[14:17], v[138:141], v[232:235], v[14:17]
	v_mfma_f32_16x16x32_bf16 v[62:65], v[134:137], v[212:215], v[62:65]
	v_mfma_f32_16x16x32_bf16 v[58:61], v[142:145], v[212:215], v[58:61]
	v_mfma_f32_16x16x32_bf16 v[54:57], v[134:137], v[220:223], v[54:57]
	v_mfma_f32_16x16x32_bf16 v[46:49], v[142:145], v[220:223], v[46:49]
	v_mfma_f32_16x16x32_bf16 v[38:41], v[134:137], v[228:231], v[38:41]
	v_mfma_f32_16x16x32_bf16 v[30:33], v[142:145], v[228:231], v[30:33]
	v_mfma_f32_16x16x32_bf16 v[22:25], v[134:137], v[236:239], v[22:25]
	v_mfma_f32_16x16x32_bf16 v[14:17], v[142:145], v[236:239], v[14:17]
	v_mfma_f32_16x16x32_bf16 v[50:53], v[178:181], v[208:211], v[50:53]
	v_mfma_f32_16x16x32_bf16 v[42:45], v[200:203], v[208:211], v[42:45]
	v_mfma_f32_16x16x32_bf16 v[34:37], v[178:181], v[216:219], v[34:37]
	v_mfma_f32_16x16x32_bf16 v[26:29], v[200:203], v[216:219], v[26:29]
	v_mfma_f32_16x16x32_bf16 v[18:21], v[178:181], v[224:227], v[18:21]
	v_mfma_f32_16x16x32_bf16 v[10:13], v[200:203], v[224:227], v[10:13]
	v_mfma_f32_16x16x32_bf16 v[6:9], v[178:181], v[232:235], v[6:9]
	v_mfma_f32_16x16x32_bf16 v[2:5], v[200:203], v[232:235], v[2:5]
	v_mfma_f32_16x16x32_bf16 v[50:53], v[182:185], v[212:215], v[50:53]
	v_mfma_f32_16x16x32_bf16 v[42:45], v[204:207], v[212:215], v[42:45]
	v_mfma_f32_16x16x32_bf16 v[34:37], v[182:185], v[220:223], v[34:37]
	v_mfma_f32_16x16x32_bf16 v[26:29], v[204:207], v[220:223], v[26:29]
	v_mfma_f32_16x16x32_bf16 v[18:21], v[182:185], v[228:231], v[18:21]
	v_mfma_f32_16x16x32_bf16 v[10:13], v[204:207], v[228:231], v[10:13]
	v_mfma_f32_16x16x32_bf16 v[6:9], v[182:185], v[236:239], v[6:9]
	v_mfma_f32_16x16x32_bf16 v[2:5], v[204:207], v[236:239], v[2:5]
	s_setprio 0
	s_barrier
; #define PG8_STAGE(bufoff, gbase, voff) do { _Pragma("unroll") for (int _i = 0; _i < 2; ++_i) \
;         __builtin_amdgcn_global_load_lds((const unsigned*)((const char*)(gbase) + (voff)[_i]), (PG8_LAS unsigned*)(lds + (bufoff) + ldsw + _i * 8192), 16, 0, 0); } while (0)
; #define PG8_LDA(dst, b, h) do { _Pragma("unroll") for (int m = 0; m < 4; ++m) _Pragma("unroll") for (int k = 0; k < 2; ++k) dst[m][k] = *(const PG8_LAS bf16x8*)(lds + PG8_SA(b, h) + aoff + m * 2048 + k * 1024); } while (0)
; #define PG8_LDB(dst, b, h) do { _Pragma("unroll") for (int n = 0; n < 2; ++n) _Pragma("unroll") for (int k = 0; k < 2; ++k) dst[n][k] = *(const PG8_LAS bf16x8*)(lds + PG8_SB(b, h) + boff + n * 2048 + k * 1024); } while (0)
; #define PG8_MMA(ai, bj, At, Bt) do { __builtin_amdgcn_s_setprio(1); _Pragma("unroll") for (int m = 0; m < 4; ++m) _Pragma("unroll") for (int n = 0; n < 2; ++n) _Pragma("unroll") for (int k = 0; k < 2; ++k) \
;         acc[ai][bj][m][n] = __builtin_amdgcn_mfma_f32_16x16x32_bf16(Bt[n][k], At[m][k], acc[ai][bj][m][n], 0, 0, 0); __builtin_amdgcn_s_setprio(0); } while (0)
; #define PG8_WAIT_V(n) asm volatile("s_waitcnt vmcnt(" #n ")" ::: "memory")
; #define PG8_WAIT_L(n) asm volatile("s_waitcnt lgkmcnt(" #n ")" ::: "memory")
; #define PG8_BAR __builtin_amdgcn_s_barrier()
; #define PG8_SCHED __builtin_amdgcn_sched_barrier(0)
; template <class Epi, class Sched, bool ALIGN_EPI = false, bool SP2 = false>
; __device__ __forceinline__ void gemm_phase(PG8_LAS unsigned char* lds, const Gemm g, const Sched& S, const Epi& E) {
;     ...
;             PG8_LDB(B0, 1, 0); PG8_LDB(B1, 1, 1); PG8_SCHED; PG8_LDA(At, 1, 0); PG8_STAGE(PG8_SA(0, 1), a2 + hstep, voffA);
;             PG8_WAIT_V(8); PG8_WAIT_L(0); PG8_BAR; PG8_MMA(0, 0, At, B0); PG8_MMA(0, 1, At, B1); PG8_BAR; PG8_SCHED;
	s_add_i32 s53, 0, 0x18000
	s_add_i32 s54, 0, 0x1c000
	v_add_u32_e32 v142, s53, v162
	v_add_u32_e32 v158, s54, v162
	ds_read_b128 v[130:133], v142
	ds_read_b128 v[134:137], v142 offset:1024
	ds_read_b128 v[138:141], v142 offset:2048
	ds_read_b128 v[142:145], v142 offset:3072
	ds_read_b128 v[178:181], v158
	ds_read_b128 v[182:185], v158 offset:1024
	ds_read_b128 v[200:203], v158 offset:2048
	ds_read_b128 v[204:207], v158 offset:3072
	s_add_u32 s8, s8, 0x80000
	s_addc_u32 s9, s9, 0
	s_mov_b32 m0, s36
	v_lshl_add_u64 v[174:175], s[8:9], 0, v[150:151]
	ds_read_b128 v[208:211], v176 offset:32768
	ds_read_b128 v[212:215], v176 offset:33792
	ds_read_b128 v[216:219], v176 offset:34816
	ds_read_b128 v[220:223], v176 offset:35840
	ds_read_b128 v[224:227], v176 offset:36864
	ds_read_b128 v[228:231], v176 offset:37888
	ds_read_b128 v[232:235], v176 offset:38912
	ds_read_b128 v[236:239], v176 offset:39936
	global_load_lds_dwordx4 v[174:175], off
	v_lshl_add_u64 v[174:175], s[8:9], 0, v[148:149]
	s_mov_b32 m0, s37
	s_nop 0
	global_load_lds_dwordx4 v[174:175], off
	s_waitcnt vmcnt(8)
	s_waitcnt lgkmcnt(0)
	s_barrier
	s_setprio 1
	s_waitcnt lgkmcnt(0)
	v_mfma_f32_16x16x32_bf16 v[126:129], v[130:133], v[208:211], v[126:129]
	v_mfma_f32_16x16x32_bf16 v[122:125], v[138:141], v[208:211], v[122:125]
	v_mfma_f32_16x16x32_bf16 v[118:121], v[130:133], v[216:219], v[118:121]
	v_mfma_f32_16x16x32_bf16 v[110:113], v[138:141], v[216:219], v[110:113]
	v_mfma_f32_16x16x32_bf16 v[102:105], v[130:133], v[224:227], v[102:105]
	v_mfma_f32_16x16x32_bf16 v[94:97], v[138:141], v[224:227], v[94:97]
	v_mfma_f32_16x16x32_bf16 v[86:89], v[130:133], v[232:235], v[86:89]
	v_mfma_f32_16x16x32_bf16 v[78:81], v[138:141], v[232:235], v[78:81]
	v_mfma_f32_16x16x32_bf16 v[126:129], v[134:137], v[212:215], v[126:129]
	v_mfma_f32_16x16x32_bf16 v[122:125], v[142:145], v[212:215], v[122:125]
	v_mfma_f32_16x16x32_bf16 v[118:121], v[134:137], v[220:223], v[118:121]
	v_mfma_f32_16x16x32_bf16 v[110:113], v[142:145], v[220:223], v[110:113]
	v_mfma_f32_16x16x32_bf16 v[102:105], v[134:137], v[228:231], v[102:105]
	v_mfma_f32_16x16x32_bf16 v[94:97], v[142:145], v[228:231], v[94:97]
	v_mfma_f32_16x16x32_bf16 v[86:89], v[134:137], v[236:239], v[86:89]
	v_mfma_f32_16x16x32_bf16 v[78:81], v[142:145], v[236:239], v[78:81]
	v_mfma_f32_16x16x32_bf16 v[114:117], v[178:181], v[208:211], v[114:117]
	v_mfma_f32_16x16x32_bf16 v[106:109], v[200:203], v[208:211], v[106:109]
	v_mfma_f32_16x16x32_bf16 v[98:101], v[178:181], v[216:219], v[98:101]
	v_mfma_f32_16x16x32_bf16 v[90:93], v[200:203], v[216:219], v[90:93]
	v_mfma_f32_16x16x32_bf16 v[82:85], v[178:181], v[224:227], v[82:85]
	v_mfma_f32_16x16x32_bf16 v[74:77], v[200:203], v[224:227], v[74:77]
	v_mfma_f32_16x16x32_bf16 v[70:73], v[178:181], v[232:235], v[70:73]
	v_mfma_f32_16x16x32_bf16 v[66:69], v[200:203], v[232:235], v[66:69]
	v_mfma_f32_16x16x32_bf16 v[114:117], v[182:185], v[212:215], v[114:117]
	v_mfma_f32_16x16x32_bf16 v[106:109], v[204:207], v[212:215], v[106:109]
	v_mfma_f32_16x16x32_bf16 v[98:101], v[182:185], v[220:223], v[98:101]
	v_mfma_f32_16x16x32_bf16 v[90:93], v[204:207], v[220:223], v[90:93]
	v_mfma_f32_16x16x32_bf16 v[82:85], v[182:185], v[228:231], v[82:85]
	v_mfma_f32_16x16x32_bf16 v[74:77], v[204:207], v[228:231], v[74:77]
	v_mfma_f32_16x16x32_bf16 v[70:73], v[182:185], v[236:239], v[70:73]
	v_mfma_f32_16x16x32_bf16 v[66:69], v[204:207], v[236:239], v[66:69]
	s_setprio 0
	s_barrier
; #define PG8_STAGE(bufoff, gbase, voff) do { _Pragma("unroll") for (int _i = 0; _i < 2; ++_i) \
;         __builtin_amdgcn_global_load_lds((const unsigned*)((const char*)(gbase) + (voff)[_i]), (PG8_LAS unsigned*)(lds + (bufoff) + ldsw + _i * 8192), 16, 0, 0); } while (0)
; #define PG8_LDA(dst, b, h) do { _Pragma("unroll") for (int m = 0; m < 4; ++m) _Pragma("unroll") for (int k = 0; k < 2; ++k) dst[m][k] = *(const PG8_LAS bf16x8*)(lds + PG8_SA(b, h) + aoff + m * 2048 + k * 1024); } while (0)
; #define PG8_MMA(ai, bj, At, Bt) do { __builtin_amdgcn_s_setprio(1); _Pragma("unroll") for (int m = 0; m < 4; ++m) _Pragma("unroll") for (int n = 0; n < 2; ++n) _Pragma("unroll") for (int k = 0; k < 2; ++k) \
;         acc[ai][bj][m][n] = __builtin_amdgcn_mfma_f32_16x16x32_bf16(Bt[n][k], At[m][k], acc[ai][bj][m][n], 0, 0, 0); __builtin_amdgcn_s_setprio(0); } while (0)
; #define PG8_WAIT_V(n) asm volatile("s_waitcnt vmcnt(" #n ")" ::: "memory")
; #define PG8_WAIT_L(n) asm volatile("s_waitcnt lgkmcnt(" #n ")" ::: "memory")
; #define PG8_BAR __builtin_amdgcn_s_barrier()
; #define PG8_SCHED __builtin_amdgcn_sched_barrier(0)
; template <class Epi, class Sched, bool ALIGN_EPI = false, bool SP2 = false>
; __device__ __forceinline__ void gemm_phase(PG8_LAS unsigned char* lds, const Gemm g, const Sched& S, const Epi& E) {
;     ...
;             PG8_LDA(At, 1, 1); PG8_STAGE(PG8_SB(1, 0), b3, voffB); PG8_STAGE(PG8_SB(1, 1), b3 + hstep, voffB); PG8_STAGE(PG8_SA(1, 0), a3, voffA);
;             PG8_WAIT_V(8); PG8_WAIT_L(0); PG8_BAR; PG8_MMA(1, 0, At, B0); PG8_MMA(1, 1, At, B1); PG8_BAR; PG8_SCHED;
;     ...
;         if constexpr (ALIGN_EPI) { if (wr == 0) PG8_BAR; }
	s_add_i32 s8, s53, s33
	v_lshl_add_u64 v[156:157], v[156:157], 0, s[44:45]
	s_mov_b32 m0, s8
	ds_read_b128 v[208:211], v176 offset:49152
	ds_read_b128 v[212:215], v176 offset:50176
	ds_read_b128 v[216:219], v176 offset:51200
	ds_read_b128 v[220:223], v176 offset:52224
	ds_read_b128 v[224:227], v176 offset:53248
	ds_read_b128 v[228:231], v176 offset:54272
	ds_read_b128 v[232:235], v176 offset:55296
	ds_read_b128 v[236:239], v176 offset:56320
	global_load_lds_dwordx4 v[156:157], off
	s_add_i32 m0, s8, 0x2000
	s_add_u32 s6, s6, 0x80080
	v_lshl_add_u64 v[156:157], v[164:165], 0, s[44:45]
	s_addc_u32 s7, s7, 0
	s_add_i32 s8, s54, s33
	global_load_lds_dwordx4 v[156:157], off
	v_lshl_add_u64 v[156:157], s[6:7], 0, v[0:1]
	s_mov_b32 m0, s8
	s_nop 0
	global_load_lds_dwordx4 v[156:157], off
	v_lshl_add_u64 v[156:157], s[6:7], 0, v[146:147]
	s_add_i32 m0, s8, 0x2000
	s_nop 0
	global_load_lds_dwordx4 v[156:157], off
	v_lshl_add_u64 v[156:157], v[166:167], 0, s[44:45]
	s_mov_b32 m0, s41
	s_nop 0
	global_load_lds_dwordx4 v[156:157], off
	v_lshl_add_u64 v[156:157], v[172:173], 0, s[44:45]
	s_mov_b32 m0, s42
	s_nop 0
	global_load_lds_dwordx4 v[156:157], off
	s_waitcnt vmcnt(8)
	s_waitcnt lgkmcnt(0)
	s_barrier
	s_setprio 1
	s_waitcnt lgkmcnt(0)
	v_mfma_f32_16x16x32_bf16 v[62:65], v[130:133], v[208:211], v[62:65]
	v_mfma_f32_16x16x32_bf16 v[58:61], v[138:141], v[208:211], v[58:61]
	v_mfma_f32_16x16x32_bf16 v[54:57], v[130:133], v[216:219], v[54:57]
	v_mfma_f32_16x16x32_bf16 v[46:49], v[138:141], v[216:219], v[46:49]
	v_mfma_f32_16x16x32_bf16 v[38:41], v[130:133], v[224:227], v[38:41]
	v_mfma_f32_16x16x32_bf16 v[30:33], v[138:141], v[224:227], v[30:33]
	v_mfma_f32_16x16x32_bf16 v[22:25], v[130:133], v[232:235], v[22:25]
	v_mfma_f32_16x16x32_bf16 v[14:17], v[138:141], v[232:235], v[14:17]
	v_mfma_f32_16x16x32_bf16 v[62:65], v[134:137], v[212:215], v[62:65]
	v_mfma_f32_16x16x32_bf16 v[58:61], v[142:145], v[212:215], v[58:61]
	v_mfma_f32_16x16x32_bf16 v[54:57], v[134:137], v[220:223], v[54:57]
	v_mfma_f32_16x16x32_bf16 v[46:49], v[142:145], v[220:223], v[46:49]
	v_mfma_f32_16x16x32_bf16 v[38:41], v[134:137], v[228:231], v[38:41]
	v_mfma_f32_16x16x32_bf16 v[30:33], v[142:145], v[228:231], v[30:33]
	v_mfma_f32_16x16x32_bf16 v[22:25], v[134:137], v[236:239], v[22:25]
	v_mfma_f32_16x16x32_bf16 v[14:17], v[142:145], v[236:239], v[14:17]
	v_mfma_f32_16x16x32_bf16 v[50:53], v[178:181], v[208:211], v[50:53]
	v_mfma_f32_16x16x32_bf16 v[42:45], v[200:203], v[208:211], v[42:45]
	v_mfma_f32_16x16x32_bf16 v[34:37], v[178:181], v[216:219], v[34:37]
	v_mfma_f32_16x16x32_bf16 v[26:29], v[200:203], v[216:219], v[26:29]
	v_mfma_f32_16x16x32_bf16 v[18:21], v[178:181], v[224:227], v[18:21]
	v_mfma_f32_16x16x32_bf16 v[10:13], v[200:203], v[224:227], v[10:13]
	v_mfma_f32_16x16x32_bf16 v[6:9], v[178:181], v[232:235], v[6:9]
	v_mfma_f32_16x16x32_bf16 v[2:5], v[200:203], v[232:235], v[2:5]
	v_mfma_f32_16x16x32_bf16 v[50:53], v[182:185], v[212:215], v[50:53]
	v_mfma_f32_16x16x32_bf16 v[42:45], v[204:207], v[212:215], v[42:45]
	v_mfma_f32_16x16x32_bf16 v[34:37], v[182:185], v[220:223], v[34:37]
	v_mfma_f32_16x16x32_bf16 v[26:29], v[204:207], v[220:223], v[26:29]
	v_mfma_f32_16x16x32_bf16 v[18:21], v[182:185], v[228:231], v[18:21]
	v_mfma_f32_16x16x32_bf16 v[10:13], v[204:207], v[228:231], v[10:13]
	v_mfma_f32_16x16x32_bf16 v[6:9], v[182:185], v[236:239], v[6:9]
	v_mfma_f32_16x16x32_bf16 v[2:5], v[204:207], v[236:239], v[2:5]
	s_setprio 0
	s_barrier
	s_add_i32 s52, s52, 2
	s_add_u32 s4, s4, 0x100
	s_addc_u32 s5, s5, 0
	s_add_u32 s28, s28, 0x100
	s_addc_u32 s29, s29, 0
	s_cmp_gt_u32 s52, 29
	s_cbranch_scc0 .LBB0_115
	s_and_b64 vcc, exec, s[16:17]
	s_cbranch_vccz .LBB0_118
	s_barrier

;     __device__ bool next(int i, Unit& u) const { const int j = first + i * G; if (j >= count) return false; u.pm = j / nN; u.pn = j % nN; return true; }
; #define PG8_STAGE(bufoff, gbase, voff) do { _Pragma("unroll") for (int _i = 0; _i < 2; ++_i) \
;         __builtin_amdgcn_global_load_lds((const unsigned*)((const char*)(gbase) + (voff)[_i]), (PG8_LAS unsigned*)(lds + (bufoff) + ldsw + _i * 8192), 16, 0, 0); } while (0)
; #define PG8_LDA(dst, b, h) do { _Pragma("unroll") for (int m = 0; m < 4; ++m) _Pragma("unroll") for (int k = 0; k < 2; ++k) dst[m][k] = *(const PG8_LAS bf16x8*)(lds + PG8_SA(b, h) + aoff + m * 2048 + k * 1024); } while (0)
; #define PG8_LDB(dst, b, h) do { _Pragma("unroll") for (int n = 0; n < 2; ++n) _Pragma("unroll") for (int k = 0; k < 2; ++k) dst[n][k] = *(const PG8_LAS bf16x8*)(lds + PG8_SB(b, h) + boff + n * 2048 + k * 1024); } while (0)
; #define PG8_WAIT_V(n) asm volatile("s_waitcnt vmcnt(" #n ")" ::: "memory")
; #define PG8_WAIT_L(n) asm volatile("s_waitcnt lgkmcnt(" #n ")" ::: "memory")
; #define PG8_BAR __builtin_amdgcn_s_barrier()
; #define PG8_SCHED __builtin_amdgcn_sched_barrier(0)
; template <class Epi, class Sched, bool ALIGN_EPI = false, bool SP2 = false>
; __device__ __forceinline__ void gemm_phase(PG8_LAS unsigned char* lds, const Gemm g, const Sched& S, const Epi& E) {
;     ...
;         const bool has_next = S.next(ui + 1, nxt);
;         const char* nA = has_next ? (const char*)g.A + (size_t)nxt.pm * tstep : cA; const char* nB = has_next ? (const char*)g.Bt + (size_t)nxt.pn * tstep : cB;
;         for (int t = 0; t < nt; t += 2) {
;             const bool last = (t == nt - 2);
;             const char* a1 = cA + (size_t)(t + 1) * kstep;
;             const char* a2 = last ? nA : cA + (size_t)(t + 2) * kstep; const char* b2 = last ? nB : cB + (size_t)(t + 2) * kstep;
;             const char* a3 = a2 + kstep; const char* b3 = b2 + kstep;
;             if (last && has_next) S.a_ready(nxt);
;             if constexpr (SP2) {
;             PG8_LDB(B0, 0, 0); PG8_LDB(B1, 0, 1); PG8_SCHED; PG8_LDA(At, 0, 0); PG8_STAGE(PG8_SA(1, 1), a1 + hstep, voffA);
;             PG8_WAIT_V(8); PG8_WAIT_L(0); PG8_BAR; PG8_MMA(0, 0, At, B0); PG8_MMA(0, 1, At, B1); PG8_BAR; PG8_SCHED;
;             PG8_LDA(At, 0, 1); PG8_STAGE(PG8_SB(0, 0), b2, voffB); PG8_STAGE(PG8_SB(0, 1), b2 + hstep, voffB); PG8_STAGE(PG8_SA(0, 0), a2, voffA);
.LBB0_825:
	s_add_u32 s41, s14, 0x100
	s_addc_u32 s42, s15, 0
	s_ashr_i32 s9, s8, 31
	s_lshl_b64 s[10:11], s[8:9], 20
	v_readlane_b32 s7, v253, 53
	s_add_u32 s12, s7, s10
	v_readlane_b32 s7, v253, 54
	s_addc_u32 s13, s7, s11
	s_and_b64 s[10:11], s[2:3], exec
	s_cselect_b32 s9, s13, s5
	s_cselect_b32 s43, s12, s4
	s_ashr_i32 s7, s6, 31
	s_lshl_b64 s[10:11], s[6:7], 20
	s_add_u32 s10, s27, s10
	s_addc_u32 s11, s28, s11
	s_and_b64 s[16:17], s[2:3], exec
	s_cselect_b32 s7, s11, s15
	s_cselect_b32 s46, s10, s14
	s_add_u32 s14, s4, 0x80080
	s_addc_u32 s15, s5, 0
	v_lshl_add_u64 v[140:141], s[14:15], 0, v[136:137]
	v_lshl_add_u64 v[142:143], s[14:15], 0, v[138:139]
	s_mov_b32 s47, -2
	s_mov_b64 s[14:15], 0
	.p2align 6
.LBB0_826:
	s_add_u32 s16, s4, s14
	s_addc_u32 s17, s5, s15
	s_add_u32 s16, s16, 0x100
	s_addc_u32 s17, s17, 0
	s_add_u32 s48, s41, s14
	s_addc_u32 s49, s42, s15
	s_add_i32 s50, 0, 0x10000
	s_cmpk_eq_i32 s14, 0xf00
	s_cselect_b32 s19, s9, s17
	s_cselect_b32 s18, s43, s16
	v_add_u32_e32 v160, s50, v144
	s_cselect_b32 s17, s7, s49
	s_cselect_b32 s16, s46, s48
	s_add_i32 s51, 0, 0x14000
	ds_read_b128 v[146:149], v160
	ds_read_b128 v[150:153], v160 offset:1024
	ds_read_b128 v[156:159], v160 offset:2048
	ds_read_b128 v[180:183], v160 offset:3072
	v_add_u32_e32 v160, s51, v144
	ds_read_b128 v[200:203], v160
	ds_read_b128 v[204:207], v160 offset:1024
	ds_read_b128 v[208:211], v160 offset:2048
	ds_read_b128 v[212:215], v160 offset:3072
	v_lshl_add_u64 v[160:161], v[140:141], 0, s[14:15]
	s_add_i32 m0, s30, 0xc000
	ds_read_b128 v[216:219], v145
	ds_read_b128 v[220:223], v145 offset:1024
	ds_read_b128 v[224:227], v145 offset:2048
	ds_read_b128 v[228:231], v145 offset:3072
	ds_read_b128 v[232:235], v145 offset:4096
	ds_read_b128 v[236:239], v145 offset:5120
	ds_read_b128 v[240:243], v145 offset:6144
	ds_read_b128 v[244:247], v145 offset:7168
	global_load_lds_dwordx4 v[160:161], off
	v_lshl_add_u64 v[160:161], v[142:143], 0, s[14:15]
	s_add_i32 m0, s30, 0xe000
	s_nop 0
	global_load_lds_dwordx4 v[160:161], off
	s_waitcnt vmcnt(8)
	s_waitcnt lgkmcnt(0)
	s_barrier
	s_setprio 1
	s_waitcnt lgkmcnt(0)
	v_mfma_f32_16x16x32_bf16 v[126:129], v[146:149], v[216:219], v[126:129]
	v_mfma_f32_16x16x32_bf16 v[122:125], v[156:159], v[216:219], v[122:125]
	v_mfma_f32_16x16x32_bf16 v[110:113], v[146:149], v[224:227], v[110:113]
	v_mfma_f32_16x16x32_bf16 v[106:109], v[156:159], v[224:227], v[106:109]
	v_mfma_f32_16x16x32_bf16 v[94:97], v[146:149], v[232:235], v[94:97]
	v_mfma_f32_16x16x32_bf16 v[90:93], v[156:159], v[232:235], v[90:93]
	v_mfma_f32_16x16x32_bf16 v[78:81], v[146:149], v[240:243], v[78:81]
	v_mfma_f32_16x16x32_bf16 v[74:77], v[156:159], v[240:243], v[74:77]
	v_mfma_f32_16x16x32_bf16 v[126:129], v[150:153], v[220:223], v[126:129]
	v_mfma_f32_16x16x32_bf16 v[122:125], v[180:183], v[220:223], v[122:125]
	v_mfma_f32_16x16x32_bf16 v[110:113], v[150:153], v[228:231], v[110:113]
	v_mfma_f32_16x16x32_bf16 v[106:109], v[180:183], v[228:231], v[106:109]
	v_mfma_f32_16x16x32_bf16 v[94:97], v[150:153], v[236:239], v[94:97]
	v_mfma_f32_16x16x32_bf16 v[90:93], v[180:183], v[236:239], v[90:93]
	v_mfma_f32_16x16x32_bf16 v[78:81], v[150:153], v[244:247], v[78:81]
	v_mfma_f32_16x16x32_bf16 v[74:77], v[180:183], v[244:247], v[74:77]
	v_mfma_f32_16x16x32_bf16 v[118:121], v[200:203], v[216:219], v[118:121]
	v_mfma_f32_16x16x32_bf16 v[114:117], v[208:211], v[216:219], v[114:117]
	v_mfma_f32_16x16x32_bf16 v[102:105], v[200:203], v[224:227], v[102:105]
	v_mfma_f32_16x16x32_bf16 v[98:101], v[208:211], v[224:227], v[98:101]
	v_mfma_f32_16x16x32_bf16 v[86:89], v[200:203], v[232:235], v[86:89]
	v_mfma_f32_16x16x32_bf16 v[82:85], v[208:211], v[232:235], v[82:85]
	v_mfma_f32_16x16x32_bf16 v[70:73], v[200:203], v[240:243], v[70:73]
	v_mfma_f32_16x16x32_bf16 v[66:69], v[208:211], v[240:243], v[66:69]
	v_mfma_f32_16x16x32_bf16 v[118:121], v[204:207], v[220:223], v[118:121]
	v_mfma_f32_16x16x32_bf16 v[114:117], v[212:215], v[220:223], v[114:117]
	v_mfma_f32_16x16x32_bf16 v[102:105], v[204:207], v[228:231], v[102:105]
	v_mfma_f32_16x16x32_bf16 v[98:101], v[212:215], v[228:231], v[98:101]
	v_mfma_f32_16x16x32_bf16 v[86:89], v[204:207], v[236:239], v[86:89]
	v_mfma_f32_16x16x32_bf16 v[82:85], v[212:215], v[236:239], v[82:85]
	v_mfma_f32_16x16x32_bf16 v[70:73], v[204:207], v[244:247], v[70:73]
	v_mfma_f32_16x16x32_bf16 v[66:69], v[212:215], v[244:247], v[66:69]
	s_setprio 0
	s_barrier
	s_add_i32 s48, s50, s29
	v_lshl_add_u64 v[160:161], s[16:17], 0, v[0:1]
	s_mov_b32 m0, s48
	ds_read_b128 v[216:219], v145 offset:16384
	ds_read_b128 v[220:223], v145 offset:17408
	ds_read_b128 v[224:227], v145 offset:18432
	ds_read_b128 v[228:231], v145 offset:19456
	ds_read_b128 v[232:235], v145 offset:20480
	ds_read_b128 v[236:239], v145 offset:21504
	ds_read_b128 v[240:243], v145 offset:22528
	ds_read_b128 v[244:247], v145 offset:23552
	global_load_lds_dwordx4 v[160:161], off
	s_add_i32 m0, s48, 0x2000
	s_add_u32 s48, s16, 0x80000
	v_lshl_add_u64 v[164:165], s[16:17], 0, v[130:131]
	s_addc_u32 s49, s17, 0
	s_add_i32 s50, s51, s29
	global_load_lds_dwordx4 v[164:165], off
	v_lshl_add_u64 v[166:167], s[48:49], 0, v[0:1]
	s_mov_b32 m0, s50
	v_lshl_add_u64 v[172:173], s[18:19], 0, v[132:133]
	global_load_lds_dwordx4 v[166:167], off
	v_lshl_add_u64 v[166:167], s[48:49], 0, v[130:131]
	s_add_i32 m0, s50, 0x2000
	s_nop 0
	global_load_lds_dwordx4 v[166:167], off
	v_lshl_add_u64 v[166:167], s[18:19], 0, v[134:135]
	s_mov_b32 m0, s30
	s_nop 0
	global_load_lds_dwordx4 v[166:167], off
	s_mov_b32 m0, s31
	s_nop 0
	global_load_lds_dwordx4 v[172:173], off
	s_waitcnt vmcnt(8)
	s_waitcnt lgkmcnt(0)
	s_barrier
; #define PG8_STAGE(bufoff, gbase, voff) do { _Pragma("unroll") for (int _i = 0; _i < 2; ++_i) \
;         __builtin_amdgcn_global_load_lds((const unsigned*)((const char*)(gbase) + (voff)[_i]), (PG8_LAS unsigned*)(lds + (bufoff) + ldsw + _i * 8192), 16, 0, 0); } while (0)
; #define PG8_LDA(dst, b, h) do { _Pragma("unroll") for (int m = 0; m < 4; ++m) _Pragma("unroll") for (int k = 0; k < 2; ++k) dst[m][k] = *(const PG8_LAS bf16x8*)(lds + PG8_SA(b, h) + aoff + m * 2048 + k * 1024); } while (0)
; #define PG8_LDB(dst, b, h) do { _Pragma("unroll") for (int n = 0; n < 2; ++n) _Pragma("unroll") for (int k = 0; k < 2; ++k) dst[n][k] = *(const PG8_LAS bf16x8*)(lds + PG8_SB(b, h) + boff + n * 2048 + k * 1024); } while (0)
; #define PG8_MMA(ai, bj, At, Bt) do { __builtin_amdgcn_s_setprio(1); _Pragma("unroll") for (int m = 0; m < 4; ++m) _Pragma("unroll") for (int n = 0; n < 2; ++n) _Pragma("unroll") for (int k = 0; k < 2; ++k) \
;         acc[ai][bj][m][n] = __builtin_amdgcn_mfma_f32_16x16x32_bf16(Bt[n][k], At[m][k], acc[ai][bj][m][n], 0, 0, 0); __builtin_amdgcn_s_setprio(0); } while (0)
; #define PG8_WAIT_V(n) asm volatile("s_waitcnt vmcnt(" #n ")" ::: "memory")
; #define PG8_WAIT_L(n) asm volatile("s_waitcnt lgkmcnt(" #n ")" ::: "memory")
; #define PG8_BAR __builtin_amdgcn_s_barrier()
; #define PG8_SCHED __builtin_amdgcn_sched_barrier(0)
; template <class Epi, class Sched, bool ALIGN_EPI = false, bool SP2 = false>
; __device__ __forceinline__ void gemm_phase(PG8_LAS unsigned char* lds, const Gemm g, const Sched& S, const Epi& E) {
;     ...
;             PG8_WAIT_V(8); PG8_WAIT_L(0); PG8_BAR; PG8_MMA(1, 0, At, B0); PG8_MMA(1, 1, At, B1); PG8_BAR; PG8_SCHED;
;             PG8_LDB(B0, 1, 0); PG8_LDB(B1, 1, 1); PG8_SCHED; PG8_LDA(At, 1, 0); PG8_STAGE(PG8_SA(0, 1), a2 + hstep, voffA);
;             PG8_WAIT_V(8); PG8_WAIT_L(0); PG8_BAR; PG8_MMA(0, 0, At, B0); PG8_MMA(0, 1, At, B1); PG8_BAR; PG8_SCHED;
	s_setprio 1
	s_waitcnt lgkmcnt(0)
	v_mfma_f32_16x16x32_bf16 v[62:65], v[146:149], v[216:219], v[62:65]
	v_mfma_f32_16x16x32_bf16 v[58:61], v[156:159], v[216:219], v[58:61]
	v_mfma_f32_16x16x32_bf16 v[46:49], v[146:149], v[224:227], v[46:49]
	v_mfma_f32_16x16x32_bf16 v[42:45], v[156:159], v[224:227], v[42:45]
	v_mfma_f32_16x16x32_bf16 v[30:33], v[146:149], v[232:235], v[30:33]
	v_mfma_f32_16x16x32_bf16 v[26:29], v[156:159], v[232:235], v[26:29]
	v_mfma_f32_16x16x32_bf16 v[14:17], v[146:149], v[240:243], v[14:17]
	v_mfma_f32_16x16x32_bf16 v[10:13], v[156:159], v[240:243], v[10:13]
	v_mfma_f32_16x16x32_bf16 v[62:65], v[150:153], v[220:223], v[62:65]
	v_mfma_f32_16x16x32_bf16 v[58:61], v[180:183], v[220:223], v[58:61]
	v_mfma_f32_16x16x32_bf16 v[46:49], v[150:153], v[228:231], v[46:49]
	v_mfma_f32_16x16x32_bf16 v[42:45], v[180:183], v[228:231], v[42:45]
	v_mfma_f32_16x16x32_bf16 v[30:33], v[150:153], v[236:239], v[30:33]
	v_mfma_f32_16x16x32_bf16 v[26:29], v[180:183], v[236:239], v[26:29]
	v_mfma_f32_16x16x32_bf16 v[14:17], v[150:153], v[244:247], v[14:17]
	v_mfma_f32_16x16x32_bf16 v[10:13], v[180:183], v[244:247], v[10:13]
	v_mfma_f32_16x16x32_bf16 v[54:57], v[200:203], v[216:219], v[54:57]
	v_mfma_f32_16x16x32_bf16 v[50:53], v[208:211], v[216:219], v[50:53]
	v_mfma_f32_16x16x32_bf16 v[38:41], v[200:203], v[224:227], v[38:41]
	v_mfma_f32_16x16x32_bf16 v[34:37], v[208:211], v[224:227], v[34:37]
	v_mfma_f32_16x16x32_bf16 v[22:25], v[200:203], v[232:235], v[22:25]
	v_mfma_f32_16x16x32_bf16 v[18:21], v[208:211], v[232:235], v[18:21]
	v_mfma_f32_16x16x32_bf16 v[6:9], v[200:203], v[240:243], v[6:9]
	v_mfma_f32_16x16x32_bf16 v[2:5], v[208:211], v[240:243], v[2:5]
	v_mfma_f32_16x16x32_bf16 v[54:57], v[204:207], v[220:223], v[54:57]
	v_mfma_f32_16x16x32_bf16 v[50:53], v[212:215], v[220:223], v[50:53]
	v_mfma_f32_16x16x32_bf16 v[38:41], v[204:207], v[228:231], v[38:41]
	v_mfma_f32_16x16x32_bf16 v[34:37], v[212:215], v[228:231], v[34:37]
	v_mfma_f32_16x16x32_bf16 v[22:25], v[204:207], v[236:239], v[22:25]
	v_mfma_f32_16x16x32_bf16 v[18:21], v[212:215], v[236:239], v[18:21]
	v_mfma_f32_16x16x32_bf16 v[6:9], v[204:207], v[244:247], v[6:9]
	v_mfma_f32_16x16x32_bf16 v[2:5], v[212:215], v[244:247], v[2:5]
	s_setprio 0
	s_barrier
	s_add_i32 s48, 0, 0x18000
	v_add_u32_e32 v162, s48, v144
	s_add_i32 s49, 0, 0x1c000
	ds_read_b128 v[146:149], v162
	ds_read_b128 v[150:153], v162 offset:1024
	ds_read_b128 v[156:159], v162 offset:2048
	ds_read_b128 v[180:183], v162 offset:3072
	v_add_u32_e32 v162, s49, v144
	ds_read_b128 v[200:203], v162
	ds_read_b128 v[204:207], v162 offset:1024
	ds_read_b128 v[208:211], v162 offset:2048
	ds_read_b128 v[212:215], v162 offset:3072
	s_add_u32 s18, s18, 0x80000
	s_addc_u32 s19, s19, 0
	s_mov_b32 m0, s33
	v_lshl_add_u64 v[174:175], s[18:19], 0, v[134:135]
	ds_read_b128 v[216:219], v145 offset:32768
	ds_read_b128 v[220:223], v145 offset:33792
	ds_read_b128 v[224:227], v145 offset:34816
	ds_read_b128 v[228:231], v145 offset:35840
	ds_read_b128 v[232:235], v145 offset:36864
	ds_read_b128 v[236:239], v145 offset:37888
	ds_read_b128 v[240:243], v145 offset:38912
	ds_read_b128 v[244:247], v145 offset:39936
	global_load_lds_dwordx4 v[174:175], off
	v_lshl_add_u64 v[174:175], s[18:19], 0, v[132:133]
	s_mov_b32 m0, s34
	s_nop 0
	global_load_lds_dwordx4 v[174:175], off
	s_waitcnt vmcnt(8)
	s_waitcnt lgkmcnt(0)
	s_barrier
	s_setprio 1
	s_waitcnt lgkmcnt(0)
	v_mfma_f32_16x16x32_bf16 v[126:129], v[146:149], v[216:219], v[126:129]
	v_mfma_f32_16x16x32_bf16 v[122:125], v[156:159], v[216:219], v[122:125]
	v_mfma_f32_16x16x32_bf16 v[110:113], v[146:149], v[224:227], v[110:113]
	v_mfma_f32_16x16x32_bf16 v[106:109], v[156:159], v[224:227], v[106:109]
	v_mfma_f32_16x16x32_bf16 v[94:97], v[146:149], v[232:235], v[94:97]
	v_mfma_f32_16x16x32_bf16 v[90:93], v[156:159], v[232:235], v[90:93]
	v_mfma_f32_16x16x32_bf16 v[78:81], v[146:149], v[240:243], v[78:81]
	v_mfma_f32_16x16x32_bf16 v[74:77], v[156:159], v[240:243], v[74:77]
	v_mfma_f32_16x16x32_bf16 v[126:129], v[150:153], v[220:223], v[126:129]
	v_mfma_f32_16x16x32_bf16 v[122:125], v[180:183], v[220:223], v[122:125]
	v_mfma_f32_16x16x32_bf16 v[110:113], v[150:153], v[228:231], v[110:113]
	v_mfma_f32_16x16x32_bf16 v[106:109], v[180:183], v[228:231], v[106:109]
	v_mfma_f32_16x16x32_bf16 v[94:97], v[150:153], v[236:239], v[94:97]
	v_mfma_f32_16x16x32_bf16 v[90:93], v[180:183], v[236:239], v[90:93]
	v_mfma_f32_16x16x32_bf16 v[78:81], v[150:153], v[244:247], v[78:81]
	v_mfma_f32_16x16x32_bf16 v[74:77], v[180:183], v[244:247], v[74:77]
	v_mfma_f32_16x16x32_bf16 v[118:121], v[200:203], v[216:219], v[118:121]
	v_mfma_f32_16x16x32_bf16 v[114:117], v[208:211], v[216:219], v[114:117]
	v_mfma_f32_16x16x32_bf16 v[102:105], v[200:203], v[224:227], v[102:105]
	v_mfma_f32_16x16x32_bf16 v[98:101], v[208:211], v[224:227], v[98:101]
	v_mfma_f32_16x16x32_bf16 v[86:89], v[200:203], v[232:235], v[86:89]
	v_mfma_f32_16x16x32_bf16 v[82:85], v[208:211], v[232:235], v[82:85]
	v_mfma_f32_16x16x32_bf16 v[70:73], v[200:203], v[240:243], v[70:73]
	v_mfma_f32_16x16x32_bf16 v[66:69], v[208:211], v[240:243], v[66:69]
	v_mfma_f32_16x16x32_bf16 v[118:121], v[204:207], v[220:223], v[118:121]
	v_mfma_f32_16x16x32_bf16 v[114:117], v[212:215], v[220:223], v[114:117]
	v_mfma_f32_16x16x32_bf16 v[102:105], v[204:207], v[228:231], v[102:105]
	v_mfma_f32_16x16x32_bf16 v[98:101], v[212:215], v[228:231], v[98:101]
	v_mfma_f32_16x16x32_bf16 v[86:89], v[204:207], v[236:239], v[86:89]
	v_mfma_f32_16x16x32_bf16 v[82:85], v[212:215], v[236:239], v[82:85]
	v_mfma_f32_16x16x32_bf16 v[70:73], v[204:207], v[244:247], v[70:73]
	v_mfma_f32_16x16x32_bf16 v[66:69], v[212:215], v[244:247], v[66:69]
	s_setprio 0
	s_barrier
; #define PG8_STAGE(bufoff, gbase, voff) do { _Pragma("unroll") for (int _i = 0; _i < 2; ++_i) \
;         __builtin_amdgcn_global_load_lds((const unsigned*)((const char*)(gbase) + (voff)[_i]), (PG8_LAS unsigned*)(lds + (bufoff) + ldsw + _i * 8192), 16, 0, 0); } while (0)
; #define PG8_LDA(dst, b, h) do { _Pragma("unroll") for (int m = 0; m < 4; ++m) _Pragma("unroll") for (int k = 0; k < 2; ++k) dst[m][k] = *(const PG8_LAS bf16x8*)(lds + PG8_SA(b, h) + aoff + m * 2048 + k * 1024); } while (0)
; #define PG8_MMA(ai, bj, At, Bt) do { __builtin_amdgcn_s_setprio(1); _Pragma("unroll") for (int m = 0; m < 4; ++m) _Pragma("unroll") for (int n = 0; n < 2; ++n) _Pragma("unroll") for (int k = 0; k < 2; ++k) \
;         acc[ai][bj][m][n] = __builtin_amdgcn_mfma_f32_16x16x32_bf16(Bt[n][k], At[m][k], acc[ai][bj][m][n], 0, 0, 0); __builtin_amdgcn_s_setprio(0); } while (0)
; #define PG8_WAIT_V(n) asm volatile("s_waitcnt vmcnt(" #n ")" ::: "memory")
; #define PG8_WAIT_L(n) asm volatile("s_waitcnt lgkmcnt(" #n ")" ::: "memory")
; #define PG8_BAR __builtin_amdgcn_s_barrier()
; #define PG8_SCHED __builtin_amdgcn_sched_barrier(0)
; template <class Epi, class Sched, bool ALIGN_EPI = false, bool SP2 = false>
; __device__ __forceinline__ void gemm_phase(PG8_LAS unsigned char* lds, const Gemm g, const Sched& S, const Epi& E) {
;     ...
;             PG8_LDA(At, 1, 1); PG8_STAGE(PG8_SB(1, 0), b3, voffB); PG8_STAGE(PG8_SB(1, 1), b3 + hstep, voffB); PG8_STAGE(PG8_SA(1, 0), a3, voffA);
;             PG8_WAIT_V(8); PG8_WAIT_L(0); PG8_BAR; PG8_MMA(1, 0, At, B0); PG8_MMA(1, 1, At, B1); PG8_BAR; PG8_SCHED;
;     ...
;         if (!has_next) break;
; #pragma unroll
;         for (int a = 0; a < 2; ++a)
; #pragma unroll
;             for (int b = 0; b < 2; ++b)
; #pragma unroll
;                 for (int m = 0; m < 4; ++m)
; #pragma unroll
;                     for (int n = 0; n < 2; ++n) acc[a][b][m][n] = (f32x4){0.f, 0.f, 0.f, 0.f};
;         cur = nxt; cA = nA; cB = nB; ++ui;
	s_add_i32 s18, s48, s29
	v_lshl_add_u64 v[160:161], v[160:161], 0, s[44:45]
	s_mov_b32 m0, s18
	ds_read_b128 v[216:219], v145 offset:49152
	ds_read_b128 v[220:223], v145 offset:50176
	ds_read_b128 v[224:227], v145 offset:51200
	ds_read_b128 v[228:231], v145 offset:52224
	ds_read_b128 v[232:235], v145 offset:53248
	ds_read_b128 v[236:239], v145 offset:54272
	ds_read_b128 v[240:243], v145 offset:55296
	ds_read_b128 v[244:247], v145 offset:56320
	global_load_lds_dwordx4 v[160:161], off
	s_add_i32 m0, s18, 0x2000
	s_add_u32 s16, s16, 0x80080
	v_lshl_add_u64 v[160:161], v[164:165], 0, s[44:45]
	s_addc_u32 s17, s17, 0
	s_add_i32 s18, s49, s29
	global_load_lds_dwordx4 v[160:161], off
	v_lshl_add_u64 v[160:161], s[16:17], 0, v[0:1]
	s_mov_b32 m0, s18
	s_nop 0
	global_load_lds_dwordx4 v[160:161], off
	v_lshl_add_u64 v[160:161], s[16:17], 0, v[130:131]
	s_add_i32 m0, s18, 0x2000
	s_nop 0
	global_load_lds_dwordx4 v[160:161], off
	v_lshl_add_u64 v[160:161], v[166:167], 0, s[44:45]
	s_mov_b32 m0, s35
	s_nop 0
	global_load_lds_dwordx4 v[160:161], off
	v_lshl_add_u64 v[160:161], v[172:173], 0, s[44:45]
	s_mov_b32 m0, s36
	s_nop 0
	global_load_lds_dwordx4 v[160:161], off
	s_waitcnt vmcnt(8)
	s_waitcnt lgkmcnt(0)
	s_barrier
	s_setprio 1
	s_waitcnt lgkmcnt(0)
	v_mfma_f32_16x16x32_bf16 v[62:65], v[146:149], v[216:219], v[62:65]
	v_mfma_f32_16x16x32_bf16 v[58:61], v[156:159], v[216:219], v[58:61]
	v_mfma_f32_16x16x32_bf16 v[46:49], v[146:149], v[224:227], v[46:49]
	v_mfma_f32_16x16x32_bf16 v[42:45], v[156:159], v[224:227], v[42:45]
	v_mfma_f32_16x16x32_bf16 v[30:33], v[146:149], v[232:235], v[30:33]
	v_mfma_f32_16x16x32_bf16 v[26:29], v[156:159], v[232:235], v[26:29]
	v_mfma_f32_16x16x32_bf16 v[14:17], v[146:149], v[240:243], v[14:17]
	v_mfma_f32_16x16x32_bf16 v[10:13], v[156:159], v[240:243], v[10:13]
	v_mfma_f32_16x16x32_bf16 v[62:65], v[150:153], v[220:223], v[62:65]
	v_mfma_f32_16x16x32_bf16 v[58:61], v[180:183], v[220:223], v[58:61]
	v_mfma_f32_16x16x32_bf16 v[46:49], v[150:153], v[228:231], v[46:49]
	v_mfma_f32_16x16x32_bf16 v[42:45], v[180:183], v[228:231], v[42:45]
	v_mfma_f32_16x16x32_bf16 v[30:33], v[150:153], v[236:239], v[30:33]
	v_mfma_f32_16x16x32_bf16 v[26:29], v[180:183], v[236:239], v[26:29]
	v_mfma_f32_16x16x32_bf16 v[14:17], v[150:153], v[244:247], v[14:17]
	v_mfma_f32_16x16x32_bf16 v[10:13], v[180:183], v[244:247], v[10:13]
	v_mfma_f32_16x16x32_bf16 v[54:57], v[200:203], v[216:219], v[54:57]
	v_mfma_f32_16x16x32_bf16 v[50:53], v[208:211], v[216:219], v[50:53]
	v_mfma_f32_16x16x32_bf16 v[38:41], v[200:203], v[224:227], v[38:41]
	v_mfma_f32_16x16x32_bf16 v[34:37], v[208:211], v[224:227], v[34:37]
	v_mfma_f32_16x16x32_bf16 v[22:25], v[200:203], v[232:235], v[22:25]
	v_mfma_f32_16x16x32_bf16 v[18:21], v[208:211], v[232:235], v[18:21]
	v_mfma_f32_16x16x32_bf16 v[6:9], v[200:203], v[240:243], v[6:9]
	v_mfma_f32_16x16x32_bf16 v[2:5], v[208:211], v[240:243], v[2:5]
	v_mfma_f32_16x16x32_bf16 v[54:57], v[204:207], v[220:223], v[54:57]
	v_mfma_f32_16x16x32_bf16 v[50:53], v[212:215], v[220:223], v[50:53]
	v_mfma_f32_16x16x32_bf16 v[38:41], v[204:207], v[228:231], v[38:41]
	v_mfma_f32_16x16x32_bf16 v[34:37], v[212:215], v[228:231], v[34:37]
	v_mfma_f32_16x16x32_bf16 v[22:25], v[204:207], v[236:239], v[22:25]
	v_mfma_f32_16x16x32_bf16 v[18:21], v[212:215], v[236:239], v[18:21]
	v_mfma_f32_16x16x32_bf16 v[6:9], v[204:207], v[244:247], v[6:9]
	v_mfma_f32_16x16x32_bf16 v[2:5], v[212:215], v[244:247], v[2:5]
	s_setprio 0
	s_barrier
	s_add_i32 s47, s47, 2
	s_add_u32 s14, s14, 0x100
	s_addc_u32 s15, s15, 0
	s_cmp_gt_u32 s47, 29
	s_cbranch_scc0 .LBB0_826
	s_add_u32 s14, s41, 0xffffff00
	s_addc_u32 s15, s42, -1
	s_andn2_b64 vcc, exec, s[2:3]
	s_cbranch_vccnz .LBB0_817
	v_mov_b32_e32 v2, 0
	s_mov_b32 s25, s6
	s_mov_b32 s24, s8
	s_mov_b64 s[4:5], s[12:13]
	s_mov_b32 s37, s40
	v_mov_b32_e32 v3, v2
	v_mov_b32_e32 v4, v2
	v_mov_b32_e32 v5, v2
	v_mov_b32_e32 v6, v2
	v_mov_b32_e32 v7, v2
	v_mov_b32_e32 v8, v2
	v_mov_b32_e32 v9, v2
	v_mov_b32_e32 v18, v2
	v_mov_b32_e32 v19, v2
	v_mov_b32_e32 v20, v2
	v_mov_b32_e32 v21, v2
	v_mov_b32_e32 v22, v2
	v_mov_b32_e32 v23, v2
	v_mov_b32_e32 v24, v2
	v_mov_b32_e32 v25, v2
	v_mov_b32_e32 v34, v2
	v_mov_b32_e32 v35, v2
	v_mov_b32_e32 v36, v2
	v_mov_b32_e32 v37, v2
	v_mov_b32_e32 v38, v2
	v_mov_b32_e32 v39, v2
	v_mov_b32_e32 v40, v2
	v_mov_b32_e32 v41, v2
	v_mov_b32_e32 v50, v2
	v_mov_b32_e32 v51, v2
	v_mov_b32_e32 v52, v2
	v_mov_b32_e32 v53, v2
	v_mov_b32_e32 v54, v2
	v_mov_b32_e32 v55, v2
	v_mov_b32_e32 v56, v2
	v_mov_b32_e32 v57, v2
	v_mov_b32_e32 v10, v2
	v_mov_b32_e32 v11, v2
	v_mov_b32_e32 v12, v2
	v_mov_b32_e32 v13, v2
	v_mov_b32_e32 v14, v2
	v_mov_b32_e32 v15, v2
	v_mov_b32_e32 v16, v2
	v_mov_b32_e32 v17, v2
	v_mov_b32_e32 v26, v2
	v_mov_b32_e32 v27, v2
	v_mov_b32_e32 v28, v2
	v_mov_b32_e32 v29, v2
	v_mov_b32_e32 v30, v2
	v_mov_b32_e32 v31, v2
	v_mov_b32_e32 v32, v2
	v_mov_b32_e32 v33, v2
	v_mov_b32_e32 v42, v2
	v_mov_b32_e32 v43, v2
	v_mov_b32_e32 v44, v2
	v_mov_b32_e32 v45, v2
	v_mov_b32_e32 v46, v2
	v_mov_b32_e32 v47, v2
	v_mov_b32_e32 v48, v2
	v_mov_b32_e32 v49, v2
	v_mov_b32_e32 v58, v2
	v_mov_b32_e32 v59, v2
	v_mov_b32_e32 v60, v2
	v_mov_b32_e32 v61, v2
	v_mov_b32_e32 v62, v2
	v_mov_b32_e32 v63, v2
	v_mov_b32_e32 v64, v2
	v_mov_b32_e32 v65, v2
	v_mov_b32_e32 v66, v2
	v_mov_b32_e32 v67, v2
	v_mov_b32_e32 v68, v2
	v_mov_b32_e32 v69, v2
	v_mov_b32_e32 v70, v2
	v_mov_b32_e32 v71, v2
	v_mov_b32_e32 v72, v2
	v_mov_b32_e32 v73, v2
	v_mov_b32_e32 v82, v2
	v_mov_b32_e32 v83, v2
	v_mov_b32_e32 v84, v2
	v_mov_b32_e32 v85, v2
	v_mov_b32_e32 v86, v2
	v_mov_b32_e32 v87, v2
	v_mov_b32_e32 v88, v2
	v_mov_b32_e32 v89, v2
	v_mov_b32_e32 v98, v2
	v_mov_b32_e32 v99, v2
	v_mov_b32_e32 v100, v2
	v_mov_b32_e32 v101, v2
	v_mov_b32_e32 v102, v2
	v_mov_b32_e32 v103, v2
	v_mov_b32_e32 v104, v2
	v_mov_b32_e32 v105, v2
	v_mov_b32_e32 v114, v2
	v_mov_b32_e32 v115, v2
	v_mov_b32_e32 v116, v2
	v_mov_b32_e32 v117, v2
	v_mov_b32_e32 v118, v2
	v_mov_b32_e32 v119, v2
	v_mov_b32_e32 v120, v2
	v_mov_b32_e32 v121, v2
	v_mov_b32_e32 v74, v2
	v_mov_b32_e32 v75, v2
	v_mov_b32_e32 v76, v2
	v_mov_b32_e32 v77, v2
	v_mov_b32_e32 v78, v2
	v_mov_b32_e32 v79, v2
	v_mov_b32_e32 v80, v2
	v_mov_b32_e32 v81, v2
	v_mov_b32_e32 v90, v2
	v_mov_b32_e32 v91, v2
	v_mov_b32_e32 v92, v2
	v_mov_b32_e32 v93, v2
	v_mov_b32_e32 v94, v2
	v_mov_b32_e32 v95, v2
	v_mov_b32_e32 v96, v2
	v_mov_b32_e32 v97, v2
	v_mov_b32_e32 v106, v2
	v_mov_b32_e32 v107, v2
	v_mov_b32_e32 v108, v2
	v_mov_b32_e32 v109, v2
	v_mov_b32_e32 v110, v2
	v_mov_b32_e32 v111, v2
	v_mov_b32_e32 v112, v2
	v_mov_b32_e32 v113, v2
	v_mov_b32_e32 v122, v2
	v_mov_b32_e32 v123, v2
	v_mov_b32_e32 v124, v2
	v_mov_b32_e32 v125, v2
	v_mov_b32_e32 v126, v2
	v_mov_b32_e32 v127, v2
	v_mov_b32_e32 v128, v2
	v_mov_b32_e32 v129, v2
	s_andn2_b64 vcc, exec, s[0:1]
	s_cbranch_vccnz .LBB0_818

;     __device__ bool next(int i, Unit& u) const { const int j = first + i * G; if (j >= count) return false; u.pm = j / nN; u.pn = j % nN; return true; }
; #define PG8_STAGE(bufoff, gbase, voff) do { _Pragma("unroll") for (int _i = 0; _i < 2; ++_i) \
;         __builtin_amdgcn_global_load_lds((const unsigned*)((const char*)(gbase) + (voff)[_i]), (PG8_LAS unsigned*)(lds + (bufoff) + ldsw + _i * 8192), 16, 0, 0); } while (0)
; #define PG8_LDA(dst, b, h) do { _Pragma("unroll") for (int m = 0; m < 4; ++m) _Pragma("unroll") for (int k = 0; k < 2; ++k) dst[m][k] = *(const PG8_LAS bf16x8*)(lds + PG8_SA(b, h) + aoff + m * 2048 + k * 1024); } while (0)
; #define PG8_LDB(dst, b, h) do { _Pragma("unroll") for (int n = 0; n < 2; ++n) _Pragma("unroll") for (int k = 0; k < 2; ++k) dst[n][k] = *(const PG8_LAS bf16x8*)(lds + PG8_SB(b, h) + boff + n * 2048 + k * 1024); } while (0)
; #define PG8_SCHED __builtin_amdgcn_sched_barrier(0)
; template <class Epi, class Sched, bool ALIGN_EPI = false, bool SP2 = false>
; __device__ __forceinline__ void gemm_phase(PG8_LAS unsigned char* lds, const Gemm g, const Sched& S, const Epi& E) {
;     ...
;         const bool has_next = S.next(ui + 1, nxt);
;         const char* nA = has_next ? (const char*)g.A + (size_t)nxt.pm * tstep : cA; const char* nB = has_next ? (const char*)g.Bt + (size_t)nxt.pn * tstep : cB;
;         for (int t = 0; t < nt; t += 2) {
;             const bool last = (t == nt - 2);
;             const char* a1 = cA + (size_t)(t + 1) * kstep;
;             const char* a2 = last ? nA : cA + (size_t)(t + 2) * kstep; const char* b2 = last ? nB : cB + (size_t)(t + 2) * kstep;
;             const char* a3 = a2 + kstep; const char* b3 = b2 + kstep;
;             if (last && has_next) S.a_ready(nxt);
;             if constexpr (SP2) {
;             PG8_LDB(B0, 0, 0); PG8_LDB(B1, 0, 1); PG8_SCHED; PG8_LDA(At, 0, 0); PG8_STAGE(PG8_SA(1, 1), a1 + hstep, voffA);
;     ...
; #pragma unroll
;         for (int a = 0; a < 2; ++a)
; #pragma unroll
;             for (int b = 0; b < 2; ++b)
; #pragma unroll
;                 for (int m = 0; m < 4; ++m)
; #pragma unroll
;                     for (int n = 0; n < 2; ++n) acc[a][b][m][n] = (f32x4){0.f, 0.f, 0.f, 0.f};
.LBB0_965:
	s_ashr_i32 s9, s8, 31
	s_lshl_b64 s[10:11], s[8:9], 20
	v_readlane_b32 s12, v254, 16
	v_readlane_b32 s13, v254, 17
	s_add_u32 s10, s12, s10
	s_addc_u32 s11, s13, s11
	s_and_b64 s[12:13], s[0:1], exec
	s_cselect_b32 s9, s11, s15
	s_cselect_b32 s33, s10, s14
	s_ashr_i32 s7, s6, 31
	s_lshl_b64 s[12:13], s[6:7], 20
	s_add_u32 s12, s20, s12
	s_addc_u32 s13, s21, s13
	s_and_b64 s[18:19], s[0:1], exec
	s_cselect_b32 s7, s13, s17
	s_cselect_b32 s34, s12, s16
	s_add_u32 s14, s14, 0x80080
	s_addc_u32 s15, s15, 0
	s_add_u32 s35, s16, 0x100
	v_mov_b32_e32 v2, 0
	s_addc_u32 s36, s17, 0
	s_mov_b32 s37, -2
	v_mov_b32_e32 v3, v2
	v_mov_b32_e32 v4, v2
	v_mov_b32_e32 v5, v2
	v_mov_b32_e32 v10, v2
	v_mov_b32_e32 v11, v2
	v_mov_b32_e32 v12, v2
	v_mov_b32_e32 v13, v2
	v_mov_b32_e32 v18, v2
	v_mov_b32_e32 v19, v2
	v_mov_b32_e32 v20, v2
	v_mov_b32_e32 v21, v2
	v_mov_b32_e32 v26, v2
	v_mov_b32_e32 v27, v2
	v_mov_b32_e32 v28, v2
	v_mov_b32_e32 v29, v2
	v_mov_b32_e32 v34, v2
	v_mov_b32_e32 v35, v2
	v_mov_b32_e32 v36, v2
	v_mov_b32_e32 v37, v2
	v_mov_b32_e32 v42, v2
	v_mov_b32_e32 v43, v2
	v_mov_b32_e32 v44, v2
	v_mov_b32_e32 v45, v2
	v_mov_b32_e32 v50, v2
	v_mov_b32_e32 v51, v2
	v_mov_b32_e32 v52, v2
	v_mov_b32_e32 v53, v2
	v_mov_b32_e32 v58, v2
	v_mov_b32_e32 v59, v2
	v_mov_b32_e32 v60, v2
	v_mov_b32_e32 v61, v2
	v_mov_b32_e32 v6, v2
	v_mov_b32_e32 v7, v2
	v_mov_b32_e32 v8, v2
	v_mov_b32_e32 v9, v2
	v_mov_b32_e32 v14, v2
	v_mov_b32_e32 v15, v2
	v_mov_b32_e32 v16, v2
	v_mov_b32_e32 v17, v2
	v_mov_b32_e32 v22, v2
	v_mov_b32_e32 v23, v2
	v_mov_b32_e32 v24, v2
	v_mov_b32_e32 v25, v2
	v_mov_b32_e32 v30, v2
	v_mov_b32_e32 v31, v2
	v_mov_b32_e32 v32, v2
	v_mov_b32_e32 v33, v2
	v_mov_b32_e32 v38, v2
	v_mov_b32_e32 v39, v2
	v_mov_b32_e32 v40, v2
	v_mov_b32_e32 v41, v2
	v_mov_b32_e32 v46, v2
	v_mov_b32_e32 v47, v2
	v_mov_b32_e32 v48, v2
	v_mov_b32_e32 v49, v2
	v_mov_b32_e32 v54, v2
	v_mov_b32_e32 v55, v2
	v_mov_b32_e32 v56, v2
	v_mov_b32_e32 v57, v2
	v_mov_b32_e32 v62, v2
	v_mov_b32_e32 v63, v2
	v_mov_b32_e32 v64, v2
	v_mov_b32_e32 v65, v2
	v_mov_b32_e32 v66, v2
	v_mov_b32_e32 v67, v2
	v_mov_b32_e32 v68, v2
	v_mov_b32_e32 v69, v2
	v_mov_b32_e32 v74, v2
	v_mov_b32_e32 v75, v2
	v_mov_b32_e32 v76, v2
	v_mov_b32_e32 v77, v2
	v_mov_b32_e32 v82, v2
	v_mov_b32_e32 v83, v2
	v_mov_b32_e32 v84, v2
	v_mov_b32_e32 v85, v2
	v_mov_b32_e32 v90, v2
	v_mov_b32_e32 v91, v2
	v_mov_b32_e32 v92, v2
	v_mov_b32_e32 v93, v2
	v_mov_b32_e32 v98, v2
	v_mov_b32_e32 v99, v2
	v_mov_b32_e32 v100, v2
	v_mov_b32_e32 v101, v2
	v_mov_b32_e32 v106, v2
	v_mov_b32_e32 v107, v2
	v_mov_b32_e32 v108, v2
	v_mov_b32_e32 v109, v2
	v_mov_b32_e32 v114, v2
	v_mov_b32_e32 v115, v2
	v_mov_b32_e32 v116, v2
	v_mov_b32_e32 v117, v2
	v_mov_b32_e32 v122, v2
	v_mov_b32_e32 v123, v2
	v_mov_b32_e32 v124, v2
	v_mov_b32_e32 v125, v2
	v_mov_b32_e32 v70, v2
	v_mov_b32_e32 v71, v2
	v_mov_b32_e32 v72, v2
	v_mov_b32_e32 v73, v2
	v_mov_b32_e32 v78, v2
	v_mov_b32_e32 v79, v2
	v_mov_b32_e32 v80, v2
	v_mov_b32_e32 v81, v2
	v_mov_b32_e32 v86, v2
	v_mov_b32_e32 v87, v2
	v_mov_b32_e32 v88, v2
	v_mov_b32_e32 v89, v2
	v_mov_b32_e32 v94, v2
	v_mov_b32_e32 v95, v2
	v_mov_b32_e32 v96, v2
	v_mov_b32_e32 v97, v2
	v_mov_b32_e32 v102, v2
	v_mov_b32_e32 v103, v2
	v_mov_b32_e32 v104, v2
	v_mov_b32_e32 v105, v2
	v_mov_b32_e32 v110, v2
	v_mov_b32_e32 v111, v2
	v_mov_b32_e32 v112, v2
	v_mov_b32_e32 v113, v2
	v_mov_b32_e32 v118, v2
	v_mov_b32_e32 v119, v2
	v_mov_b32_e32 v120, v2
	v_mov_b32_e32 v121, v2
	v_mov_b32_e32 v126, v2
	v_mov_b32_e32 v127, v2
	v_mov_b32_e32 v128, v2
	v_mov_b32_e32 v129, v2
	.p2align 6
.LBB0_966:
	s_add_u32 s16, s14, 0xfff80080
	s_addc_u32 s17, s15, -1
	s_add_i32 s40, 0, 0x10000
	s_cmp_eq_u32 s37, 28
	s_cselect_b32 s19, s9, s17
	s_cselect_b32 s18, s33, s16
	s_cselect_b32 s17, s7, s36
	s_cselect_b32 s16, s34, s35
	s_add_i32 s42, 0, 0x14000
	v_add_u32_e32 v156, s40, v145
	v_add_u32_e32 v160, s42, v145
	ds_read_b128 v[140:143], v156
	ds_read_b128 v[148:151], v156 offset:1024
	ds_read_b128 v[152:155], v156 offset:2048
	ds_read_b128 v[156:159], v156 offset:3072
	ds_read_b128 v[164:167], v160
	ds_read_b128 v[172:175], v160 offset:1024
	ds_read_b128 v[176:179], v160 offset:2048
	ds_read_b128 v[180:183], v160 offset:3072
	v_lshl_add_u64 v[160:161], s[14:15], 0, v[136:137]
	s_add_i32 m0, s23, 0xc000
	ds_read_b128 v[200:203], v147
	ds_read_b128 v[204:207], v147 offset:1024
	ds_read_b128 v[208:211], v147 offset:2048
	ds_read_b128 v[212:215], v147 offset:3072
	ds_read_b128 v[216:219], v147 offset:4096
	ds_read_b128 v[220:223], v147 offset:5120
	ds_read_b128 v[224:227], v147 offset:6144
	ds_read_b128 v[228:231], v147 offset:7168
	global_load_lds_dwordx4 v[160:161], off
	v_lshl_add_u64 v[160:161], s[14:15], 0, v[138:139]
	s_add_i32 m0, s23, 0xe000
	s_nop 0
	global_load_lds_dwordx4 v[160:161], off
	s_waitcnt vmcnt(8)
	s_waitcnt lgkmcnt(0)
	s_barrier
; #define PG8_STAGE(bufoff, gbase, voff) do { _Pragma("unroll") for (int _i = 0; _i < 2; ++_i) \
;         __builtin_amdgcn_global_load_lds((const unsigned*)((const char*)(gbase) + (voff)[_i]), (PG8_LAS unsigned*)(lds + (bufoff) + ldsw + _i * 8192), 16, 0, 0); } while (0)
; #define PG8_LDA(dst, b, h) do { _Pragma("unroll") for (int m = 0; m < 4; ++m) _Pragma("unroll") for (int k = 0; k < 2; ++k) dst[m][k] = *(const PG8_LAS bf16x8*)(lds + PG8_SA(b, h) + aoff + m * 2048 + k * 1024); } while (0)
; #define PG8_MMA(ai, bj, At, Bt) do { __builtin_amdgcn_s_setprio(1); _Pragma("unroll") for (int m = 0; m < 4; ++m) _Pragma("unroll") for (int n = 0; n < 2; ++n) _Pragma("unroll") for (int k = 0; k < 2; ++k) \
;         acc[ai][bj][m][n] = __builtin_amdgcn_mfma_f32_16x16x32_bf16(Bt[n][k], At[m][k], acc[ai][bj][m][n], 0, 0, 0); __builtin_amdgcn_s_setprio(0); } while (0)
; #define PG8_WAIT_V(n) asm volatile("s_waitcnt vmcnt(" #n ")" ::: "memory")
; #define PG8_WAIT_L(n) asm volatile("s_waitcnt lgkmcnt(" #n ")" ::: "memory")
; #define PG8_BAR __builtin_amdgcn_s_barrier()
; #define PG8_SCHED __builtin_amdgcn_sched_barrier(0)
; template <class Epi, class Sched, bool ALIGN_EPI = false, bool SP2 = false>
; __device__ __forceinline__ void gemm_phase(PG8_LAS unsigned char* lds, const Gemm g, const Sched& S, const Epi& E) {
;     ...
;             PG8_WAIT_V(8); PG8_WAIT_L(0); PG8_BAR; PG8_MMA(0, 0, At, B0); PG8_MMA(0, 1, At, B1); PG8_BAR; PG8_SCHED;
;             PG8_LDA(At, 0, 1); PG8_STAGE(PG8_SB(0, 0), b2, voffB); PG8_STAGE(PG8_SB(0, 1), b2 + hstep, voffB); PG8_STAGE(PG8_SA(0, 0), a2, voffA);
;             PG8_WAIT_V(8); PG8_WAIT_L(0); PG8_BAR; PG8_MMA(1, 0, At, B0); PG8_MMA(1, 1, At, B1); PG8_BAR; PG8_SCHED;
	s_setprio 1
	s_waitcnt lgkmcnt(0)
	v_mfma_f32_16x16x32_bf16 v[126:129], v[140:143], v[200:203], v[126:129]
	v_mfma_f32_16x16x32_bf16 v[118:121], v[152:155], v[200:203], v[118:121]
	v_mfma_f32_16x16x32_bf16 v[110:113], v[140:143], v[208:211], v[110:113]
	v_mfma_f32_16x16x32_bf16 v[102:105], v[152:155], v[208:211], v[102:105]
	v_mfma_f32_16x16x32_bf16 v[94:97], v[140:143], v[216:219], v[94:97]
	v_mfma_f32_16x16x32_bf16 v[86:89], v[152:155], v[216:219], v[86:89]
	v_mfma_f32_16x16x32_bf16 v[78:81], v[140:143], v[224:227], v[78:81]
	v_mfma_f32_16x16x32_bf16 v[70:73], v[152:155], v[224:227], v[70:73]
	v_mfma_f32_16x16x32_bf16 v[126:129], v[148:151], v[204:207], v[126:129]
	v_mfma_f32_16x16x32_bf16 v[118:121], v[156:159], v[204:207], v[118:121]
	v_mfma_f32_16x16x32_bf16 v[110:113], v[148:151], v[212:215], v[110:113]
	v_mfma_f32_16x16x32_bf16 v[102:105], v[156:159], v[212:215], v[102:105]
	v_mfma_f32_16x16x32_bf16 v[94:97], v[148:151], v[220:223], v[94:97]
	v_mfma_f32_16x16x32_bf16 v[86:89], v[156:159], v[220:223], v[86:89]
	v_mfma_f32_16x16x32_bf16 v[78:81], v[148:151], v[228:231], v[78:81]
	v_mfma_f32_16x16x32_bf16 v[70:73], v[156:159], v[228:231], v[70:73]
	v_mfma_f32_16x16x32_bf16 v[122:125], v[164:167], v[200:203], v[122:125]
	v_mfma_f32_16x16x32_bf16 v[114:117], v[176:179], v[200:203], v[114:117]
	v_mfma_f32_16x16x32_bf16 v[106:109], v[164:167], v[208:211], v[106:109]
	v_mfma_f32_16x16x32_bf16 v[98:101], v[176:179], v[208:211], v[98:101]
	v_mfma_f32_16x16x32_bf16 v[90:93], v[164:167], v[216:219], v[90:93]
	v_mfma_f32_16x16x32_bf16 v[82:85], v[176:179], v[216:219], v[82:85]
	v_mfma_f32_16x16x32_bf16 v[74:77], v[164:167], v[224:227], v[74:77]
	v_mfma_f32_16x16x32_bf16 v[66:69], v[176:179], v[224:227], v[66:69]
	v_mfma_f32_16x16x32_bf16 v[122:125], v[172:175], v[204:207], v[122:125]
	v_mfma_f32_16x16x32_bf16 v[114:117], v[180:183], v[204:207], v[114:117]
	v_mfma_f32_16x16x32_bf16 v[106:109], v[172:175], v[212:215], v[106:109]
	v_mfma_f32_16x16x32_bf16 v[98:101], v[180:183], v[212:215], v[98:101]
	v_mfma_f32_16x16x32_bf16 v[90:93], v[172:175], v[220:223], v[90:93]
	v_mfma_f32_16x16x32_bf16 v[82:85], v[180:183], v[220:223], v[82:85]
	v_mfma_f32_16x16x32_bf16 v[74:77], v[172:175], v[228:231], v[74:77]
	v_mfma_f32_16x16x32_bf16 v[66:69], v[180:183], v[228:231], v[66:69]
	s_setprio 0
	s_barrier
	s_add_i32 s40, s40, s22
	v_lshl_add_u64 v[160:161], s[16:17], 0, v[0:1]
	s_mov_b32 m0, s40
	ds_read_b128 v[200:203], v147 offset:16384
	ds_read_b128 v[204:207], v147 offset:17408
	ds_read_b128 v[208:211], v147 offset:18432
	ds_read_b128 v[212:215], v147 offset:19456
	ds_read_b128 v[216:219], v147 offset:20480
	ds_read_b128 v[220:223], v147 offset:21504
	ds_read_b128 v[224:227], v147 offset:22528
	ds_read_b128 v[228:231], v147 offset:23552
	global_load_lds_dwordx4 v[160:161], off
	s_add_i32 m0, s40, 0x2000
	s_add_u32 s40, s16, 0x80000
	v_lshl_add_u64 v[184:185], s[16:17], 0, v[130:131]
	s_addc_u32 s41, s17, 0
	s_add_i32 s42, s42, s22
	global_load_lds_dwordx4 v[184:185], off
	v_lshl_add_u64 v[232:233], s[40:41], 0, v[0:1]
	s_mov_b32 m0, s42
	v_lshl_add_u64 v[234:235], s[18:19], 0, v[132:133]
	global_load_lds_dwordx4 v[232:233], off
	v_lshl_add_u64 v[232:233], s[40:41], 0, v[130:131]
	s_add_i32 m0, s42, 0x2000
	s_nop 0
	global_load_lds_dwordx4 v[232:233], off
	v_lshl_add_u64 v[232:233], s[18:19], 0, v[134:135]
	s_mov_b32 m0, s23
	s_nop 0
	global_load_lds_dwordx4 v[232:233], off
	s_mov_b32 m0, s24
	s_nop 0
	global_load_lds_dwordx4 v[234:235], off
	s_waitcnt vmcnt(8)
	s_waitcnt lgkmcnt(0)
	s_barrier
	s_setprio 1
	s_waitcnt lgkmcnt(0)
	v_mfma_f32_16x16x32_bf16 v[62:65], v[140:143], v[200:203], v[62:65]
	v_mfma_f32_16x16x32_bf16 v[54:57], v[152:155], v[200:203], v[54:57]
	v_mfma_f32_16x16x32_bf16 v[46:49], v[140:143], v[208:211], v[46:49]
	v_mfma_f32_16x16x32_bf16 v[38:41], v[152:155], v[208:211], v[38:41]
	v_mfma_f32_16x16x32_bf16 v[30:33], v[140:143], v[216:219], v[30:33]
	v_mfma_f32_16x16x32_bf16 v[22:25], v[152:155], v[216:219], v[22:25]
	v_mfma_f32_16x16x32_bf16 v[14:17], v[140:143], v[224:227], v[14:17]
	v_mfma_f32_16x16x32_bf16 v[6:9], v[152:155], v[224:227], v[6:9]
	v_mfma_f32_16x16x32_bf16 v[62:65], v[148:151], v[204:207], v[62:65]
	v_mfma_f32_16x16x32_bf16 v[54:57], v[156:159], v[204:207], v[54:57]
	v_mfma_f32_16x16x32_bf16 v[46:49], v[148:151], v[212:215], v[46:49]
	v_mfma_f32_16x16x32_bf16 v[38:41], v[156:159], v[212:215], v[38:41]
	v_mfma_f32_16x16x32_bf16 v[30:33], v[148:151], v[220:223], v[30:33]
	v_mfma_f32_16x16x32_bf16 v[22:25], v[156:159], v[220:223], v[22:25]
	v_mfma_f32_16x16x32_bf16 v[14:17], v[148:151], v[228:231], v[14:17]
	v_mfma_f32_16x16x32_bf16 v[6:9], v[156:159], v[228:231], v[6:9]
	v_mfma_f32_16x16x32_bf16 v[58:61], v[164:167], v[200:203], v[58:61]
	v_mfma_f32_16x16x32_bf16 v[50:53], v[176:179], v[200:203], v[50:53]
	v_mfma_f32_16x16x32_bf16 v[42:45], v[164:167], v[208:211], v[42:45]
	v_mfma_f32_16x16x32_bf16 v[34:37], v[176:179], v[208:211], v[34:37]
	v_mfma_f32_16x16x32_bf16 v[26:29], v[164:167], v[216:219], v[26:29]
	v_mfma_f32_16x16x32_bf16 v[18:21], v[176:179], v[216:219], v[18:21]
	v_mfma_f32_16x16x32_bf16 v[10:13], v[164:167], v[224:227], v[10:13]
	v_mfma_f32_16x16x32_bf16 v[2:5], v[176:179], v[224:227], v[2:5]
	v_mfma_f32_16x16x32_bf16 v[58:61], v[172:175], v[204:207], v[58:61]
	v_mfma_f32_16x16x32_bf16 v[50:53], v[180:183], v[204:207], v[50:53]
	v_mfma_f32_16x16x32_bf16 v[42:45], v[172:175], v[212:215], v[42:45]
	v_mfma_f32_16x16x32_bf16 v[34:37], v[180:183], v[212:215], v[34:37]
	v_mfma_f32_16x16x32_bf16 v[26:29], v[172:175], v[220:223], v[26:29]
	v_mfma_f32_16x16x32_bf16 v[18:21], v[180:183], v[220:223], v[18:21]
	v_mfma_f32_16x16x32_bf16 v[10:13], v[172:175], v[228:231], v[10:13]
	v_mfma_f32_16x16x32_bf16 v[2:5], v[180:183], v[228:231], v[2:5]
	s_setprio 0
	s_barrier
; #define PG8_STAGE(bufoff, gbase, voff) do { _Pragma("unroll") for (int _i = 0; _i < 2; ++_i) \
;         __builtin_amdgcn_global_load_lds((const unsigned*)((const char*)(gbase) + (voff)[_i]), (PG8_LAS unsigned*)(lds + (bufoff) + ldsw + _i * 8192), 16, 0, 0); } while (0)
; #define PG8_LDA(dst, b, h) do { _Pragma("unroll") for (int m = 0; m < 4; ++m) _Pragma("unroll") for (int k = 0; k < 2; ++k) dst[m][k] = *(const PG8_LAS bf16x8*)(lds + PG8_SA(b, h) + aoff + m * 2048 + k * 1024); } while (0)
; #define PG8_LDB(dst, b, h) do { _Pragma("unroll") for (int n = 0; n < 2; ++n) _Pragma("unroll") for (int k = 0; k < 2; ++k) dst[n][k] = *(const PG8_LAS bf16x8*)(lds + PG8_SB(b, h) + boff + n * 2048 + k * 1024); } while (0)
; #define PG8_MMA(ai, bj, At, Bt) do { __builtin_amdgcn_s_setprio(1); _Pragma("unroll") for (int m = 0; m < 4; ++m) _Pragma("unroll") for (int n = 0; n < 2; ++n) _Pragma("unroll") for (int k = 0; k < 2; ++k) \
;         acc[ai][bj][m][n] = __builtin_amdgcn_mfma_f32_16x16x32_bf16(Bt[n][k], At[m][k], acc[ai][bj][m][n], 0, 0, 0); __builtin_amdgcn_s_setprio(0); } while (0)
; #define PG8_WAIT_V(n) asm volatile("s_waitcnt vmcnt(" #n ")" ::: "memory")
; #define PG8_WAIT_L(n) asm volatile("s_waitcnt lgkmcnt(" #n ")" ::: "memory")
; #define PG8_BAR __builtin_amdgcn_s_barrier()
; #define PG8_SCHED __builtin_amdgcn_sched_barrier(0)
; template <class Epi, class Sched, bool ALIGN_EPI = false, bool SP2 = false>
; __device__ __forceinline__ void gemm_phase(PG8_LAS unsigned char* lds, const Gemm g, const Sched& S, const Epi& E) {
;     ...
;             PG8_LDB(B0, 1, 0); PG8_LDB(B1, 1, 1); PG8_SCHED; PG8_LDA(At, 1, 0); PG8_STAGE(PG8_SA(0, 1), a2 + hstep, voffA);
;             PG8_WAIT_V(8); PG8_WAIT_L(0); PG8_BAR; PG8_MMA(0, 0, At, B0); PG8_MMA(0, 1, At, B1); PG8_BAR; PG8_SCHED;
	s_add_i32 s40, 0, 0x18000
	s_add_i32 s41, 0, 0x1c000
	v_add_u32_e32 v156, s40, v145
	v_add_u32_e32 v162, s41, v145
	ds_read_b128 v[140:143], v156
	ds_read_b128 v[148:151], v156 offset:1024
	ds_read_b128 v[152:155], v156 offset:2048
	ds_read_b128 v[156:159], v156 offset:3072
	ds_read_b128 v[164:167], v162
	ds_read_b128 v[172:175], v162 offset:1024
	ds_read_b128 v[176:179], v162 offset:2048
	ds_read_b128 v[180:183], v162 offset:3072
	s_add_u32 s18, s18, 0x80000
	s_addc_u32 s19, s19, 0
	s_mov_b32 m0, s25
	v_lshl_add_u64 v[236:237], s[18:19], 0, v[134:135]
	ds_read_b128 v[200:203], v147 offset:32768
	ds_read_b128 v[204:207], v147 offset:33792
	ds_read_b128 v[208:211], v147 offset:34816
	ds_read_b128 v[212:215], v147 offset:35840
	ds_read_b128 v[216:219], v147 offset:36864
	ds_read_b128 v[220:223], v147 offset:37888
	ds_read_b128 v[224:227], v147 offset:38912
	ds_read_b128 v[228:231], v147 offset:39936
	global_load_lds_dwordx4 v[236:237], off
	v_lshl_add_u64 v[236:237], s[18:19], 0, v[132:133]
	s_mov_b32 m0, s26
	s_nop 0
	global_load_lds_dwordx4 v[236:237], off
	s_waitcnt vmcnt(8)
	s_waitcnt lgkmcnt(0)
	s_barrier
	s_setprio 1
	s_waitcnt lgkmcnt(0)
	v_mfma_f32_16x16x32_bf16 v[126:129], v[140:143], v[200:203], v[126:129]
	v_mfma_f32_16x16x32_bf16 v[118:121], v[152:155], v[200:203], v[118:121]
	v_mfma_f32_16x16x32_bf16 v[110:113], v[140:143], v[208:211], v[110:113]
	v_mfma_f32_16x16x32_bf16 v[102:105], v[152:155], v[208:211], v[102:105]
	v_mfma_f32_16x16x32_bf16 v[94:97], v[140:143], v[216:219], v[94:97]
	v_mfma_f32_16x16x32_bf16 v[86:89], v[152:155], v[216:219], v[86:89]
	v_mfma_f32_16x16x32_bf16 v[78:81], v[140:143], v[224:227], v[78:81]
	v_mfma_f32_16x16x32_bf16 v[70:73], v[152:155], v[224:227], v[70:73]
	v_mfma_f32_16x16x32_bf16 v[126:129], v[148:151], v[204:207], v[126:129]
	v_mfma_f32_16x16x32_bf16 v[118:121], v[156:159], v[204:207], v[118:121]
	v_mfma_f32_16x16x32_bf16 v[110:113], v[148:151], v[212:215], v[110:113]
	v_mfma_f32_16x16x32_bf16 v[102:105], v[156:159], v[212:215], v[102:105]
	v_mfma_f32_16x16x32_bf16 v[94:97], v[148:151], v[220:223], v[94:97]
	v_mfma_f32_16x16x32_bf16 v[86:89], v[156:159], v[220:223], v[86:89]
	v_mfma_f32_16x16x32_bf16 v[78:81], v[148:151], v[228:231], v[78:81]
	v_mfma_f32_16x16x32_bf16 v[70:73], v[156:159], v[228:231], v[70:73]
	v_mfma_f32_16x16x32_bf16 v[122:125], v[164:167], v[200:203], v[122:125]
	v_mfma_f32_16x16x32_bf16 v[114:117], v[176:179], v[200:203], v[114:117]
	v_mfma_f32_16x16x32_bf16 v[106:109], v[164:167], v[208:211], v[106:109]
	v_mfma_f32_16x16x32_bf16 v[98:101], v[176:179], v[208:211], v[98:101]
	v_mfma_f32_16x16x32_bf16 v[90:93], v[164:167], v[216:219], v[90:93]
	v_mfma_f32_16x16x32_bf16 v[82:85], v[176:179], v[216:219], v[82:85]
	v_mfma_f32_16x16x32_bf16 v[74:77], v[164:167], v[224:227], v[74:77]
	v_mfma_f32_16x16x32_bf16 v[66:69], v[176:179], v[224:227], v[66:69]
	v_mfma_f32_16x16x32_bf16 v[122:125], v[172:175], v[204:207], v[122:125]
	v_mfma_f32_16x16x32_bf16 v[114:117], v[180:183], v[204:207], v[114:117]
	v_mfma_f32_16x16x32_bf16 v[106:109], v[172:175], v[212:215], v[106:109]
	v_mfma_f32_16x16x32_bf16 v[98:101], v[180:183], v[212:215], v[98:101]
	v_mfma_f32_16x16x32_bf16 v[90:93], v[172:175], v[220:223], v[90:93]
	v_mfma_f32_16x16x32_bf16 v[82:85], v[180:183], v[220:223], v[82:85]
	v_mfma_f32_16x16x32_bf16 v[74:77], v[172:175], v[228:231], v[74:77]
	v_mfma_f32_16x16x32_bf16 v[66:69], v[180:183], v[228:231], v[66:69]
	s_setprio 0
	s_barrier
; #define PG8_STAGE(bufoff, gbase, voff) do { _Pragma("unroll") for (int _i = 0; _i < 2; ++_i) \
;         __builtin_amdgcn_global_load_lds((const unsigned*)((const char*)(gbase) + (voff)[_i]), (PG8_LAS unsigned*)(lds + (bufoff) + ldsw + _i * 8192), 16, 0, 0); } while (0)
; #define PG8_LDA(dst, b, h) do { _Pragma("unroll") for (int m = 0; m < 4; ++m) _Pragma("unroll") for (int k = 0; k < 2; ++k) dst[m][k] = *(const PG8_LAS bf16x8*)(lds + PG8_SA(b, h) + aoff + m * 2048 + k * 1024); } while (0)
; #define PG8_MMA(ai, bj, At, Bt) do { __builtin_amdgcn_s_setprio(1); _Pragma("unroll") for (int m = 0; m < 4; ++m) _Pragma("unroll") for (int n = 0; n < 2; ++n) _Pragma("unroll") for (int k = 0; k < 2; ++k) \
;         acc[ai][bj][m][n] = __builtin_amdgcn_mfma_f32_16x16x32_bf16(Bt[n][k], At[m][k], acc[ai][bj][m][n], 0, 0, 0); __builtin_amdgcn_s_setprio(0); } while (0)
; #define PG8_WAIT_V(n) asm volatile("s_waitcnt vmcnt(" #n ")" ::: "memory")
; #define PG8_WAIT_L(n) asm volatile("s_waitcnt lgkmcnt(" #n ")" ::: "memory")
; #define PG8_BAR __builtin_amdgcn_s_barrier()
; #define PG8_SCHED __builtin_amdgcn_sched_barrier(0)
; template <class Epi, class Sched, bool ALIGN_EPI = false, bool SP2 = false>
; __device__ __forceinline__ void gemm_phase(PG8_LAS unsigned char* lds, const Gemm g, const Sched& S, const Epi& E) {
;     ...
;             PG8_LDA(At, 1, 1); PG8_STAGE(PG8_SB(1, 0), b3, voffB); PG8_STAGE(PG8_SB(1, 1), b3 + hstep, voffB); PG8_STAGE(PG8_SA(1, 0), a3, voffA);
;             PG8_WAIT_V(8); PG8_WAIT_L(0); PG8_BAR; PG8_MMA(1, 0, At, B0); PG8_MMA(1, 1, At, B1); PG8_BAR; PG8_SCHED;
;     ...
;         if constexpr (ALIGN_EPI) { if (wr == 0) PG8_BAR; }
	s_add_i32 s18, s40, s22
	v_lshl_add_u64 v[160:161], v[160:161], 0, s[44:45]
	s_mov_b32 m0, s18
	ds_read_b128 v[200:203], v147 offset:49152
	ds_read_b128 v[204:207], v147 offset:50176
	ds_read_b128 v[208:211], v147 offset:51200
	ds_read_b128 v[212:215], v147 offset:52224
	ds_read_b128 v[216:219], v147 offset:53248
	ds_read_b128 v[220:223], v147 offset:54272
	ds_read_b128 v[224:227], v147 offset:55296
	ds_read_b128 v[228:231], v147 offset:56320
	global_load_lds_dwordx4 v[160:161], off
	s_add_i32 m0, s18, 0x2000
	s_add_u32 s16, s16, 0x80080
	v_lshl_add_u64 v[160:161], v[184:185], 0, s[44:45]
	s_addc_u32 s17, s17, 0
	s_add_i32 s18, s41, s22
	global_load_lds_dwordx4 v[160:161], off
	v_lshl_add_u64 v[160:161], s[16:17], 0, v[0:1]
	s_mov_b32 m0, s18
	s_nop 0
	global_load_lds_dwordx4 v[160:161], off
	v_lshl_add_u64 v[160:161], s[16:17], 0, v[130:131]
	s_add_i32 m0, s18, 0x2000
	s_nop 0
	global_load_lds_dwordx4 v[160:161], off
	v_lshl_add_u64 v[160:161], v[232:233], 0, s[44:45]
	s_mov_b32 m0, s27
	s_nop 0
	global_load_lds_dwordx4 v[160:161], off
	v_lshl_add_u64 v[160:161], v[234:235], 0, s[44:45]
	s_mov_b32 m0, s28
	s_nop 0
	global_load_lds_dwordx4 v[160:161], off
	s_waitcnt vmcnt(8)
	s_waitcnt lgkmcnt(0)
	s_barrier
	s_setprio 1
	s_waitcnt lgkmcnt(0)
	v_mfma_f32_16x16x32_bf16 v[62:65], v[140:143], v[200:203], v[62:65]
	v_mfma_f32_16x16x32_bf16 v[54:57], v[152:155], v[200:203], v[54:57]
	v_mfma_f32_16x16x32_bf16 v[46:49], v[140:143], v[208:211], v[46:49]
	v_mfma_f32_16x16x32_bf16 v[38:41], v[152:155], v[208:211], v[38:41]
	v_mfma_f32_16x16x32_bf16 v[30:33], v[140:143], v[216:219], v[30:33]
	v_mfma_f32_16x16x32_bf16 v[22:25], v[152:155], v[216:219], v[22:25]
	v_mfma_f32_16x16x32_bf16 v[14:17], v[140:143], v[224:227], v[14:17]
	v_mfma_f32_16x16x32_bf16 v[6:9], v[152:155], v[224:227], v[6:9]
	v_mfma_f32_16x16x32_bf16 v[62:65], v[148:151], v[204:207], v[62:65]
	v_mfma_f32_16x16x32_bf16 v[54:57], v[156:159], v[204:207], v[54:57]
	v_mfma_f32_16x16x32_bf16 v[46:49], v[148:151], v[212:215], v[46:49]
	v_mfma_f32_16x16x32_bf16 v[38:41], v[156:159], v[212:215], v[38:41]
	v_mfma_f32_16x16x32_bf16 v[30:33], v[148:151], v[220:223], v[30:33]
	v_mfma_f32_16x16x32_bf16 v[22:25], v[156:159], v[220:223], v[22:25]
	v_mfma_f32_16x16x32_bf16 v[14:17], v[148:151], v[228:231], v[14:17]
	v_mfma_f32_16x16x32_bf16 v[6:9], v[156:159], v[228:231], v[6:9]
	v_mfma_f32_16x16x32_bf16 v[58:61], v[164:167], v[200:203], v[58:61]
	v_mfma_f32_16x16x32_bf16 v[50:53], v[176:179], v[200:203], v[50:53]
	v_mfma_f32_16x16x32_bf16 v[42:45], v[164:167], v[208:211], v[42:45]
	v_mfma_f32_16x16x32_bf16 v[34:37], v[176:179], v[208:211], v[34:37]
	v_mfma_f32_16x16x32_bf16 v[26:29], v[164:167], v[216:219], v[26:29]
	v_mfma_f32_16x16x32_bf16 v[18:21], v[176:179], v[216:219], v[18:21]
	v_mfma_f32_16x16x32_bf16 v[10:13], v[164:167], v[224:227], v[10:13]
	v_mfma_f32_16x16x32_bf16 v[2:5], v[176:179], v[224:227], v[2:5]
	v_mfma_f32_16x16x32_bf16 v[58:61], v[172:175], v[204:207], v[58:61]
	v_mfma_f32_16x16x32_bf16 v[50:53], v[180:183], v[204:207], v[50:53]
	v_mfma_f32_16x16x32_bf16 v[42:45], v[172:175], v[212:215], v[42:45]
	v_mfma_f32_16x16x32_bf16 v[34:37], v[180:183], v[212:215], v[34:37]
	v_mfma_f32_16x16x32_bf16 v[26:29], v[172:175], v[220:223], v[26:29]
	v_mfma_f32_16x16x32_bf16 v[18:21], v[180:183], v[220:223], v[18:21]
	v_mfma_f32_16x16x32_bf16 v[10:13], v[172:175], v[228:231], v[10:13]
	v_mfma_f32_16x16x32_bf16 v[2:5], v[180:183], v[228:231], v[2:5]
	s_setprio 0
	s_barrier
	s_add_i32 s37, s37, 2
	s_add_u32 s14, s14, 0x100
	s_addc_u32 s15, s15, 0
	s_add_u32 s35, s35, 0x100
	s_addc_u32 s36, s36, 0
	s_cmp_gt_u32 s37, 29
	s_cbranch_scc0 .LBB0_966
	s_and_b64 vcc, exec, s[4:5]
	s_cbranch_vccz .LBB0_969
	s_barrier

;     __device__ bool next(int i, Unit& u) const { const int j = first + i * G; if (j >= count) return false; u.pm = j / nN; u.pn = j % nN; return true; }
; #define PG8_STAGE(bufoff, gbase, voff) do { _Pragma("unroll") for (int _i = 0; _i < 2; ++_i) \
;         __builtin_amdgcn_global_load_lds((const unsigned*)((const char*)(gbase) + (voff)[_i]), (PG8_LAS unsigned*)(lds + (bufoff) + ldsw + _i * 8192), 16, 0, 0); } while (0)
; #define PG8_LDA(dst, b, h) do { _Pragma("unroll") for (int m = 0; m < 4; ++m) _Pragma("unroll") for (int k = 0; k < 2; ++k) dst[m][k] = *(const PG8_LAS bf16x8*)(lds + PG8_SA(b, h) + aoff + m * 2048 + k * 1024); } while (0)
; #define PG8_LDB(dst, b, h) do { _Pragma("unroll") for (int n = 0; n < 2; ++n) _Pragma("unroll") for (int k = 0; k < 2; ++k) dst[n][k] = *(const PG8_LAS bf16x8*)(lds + PG8_SB(b, h) + boff + n * 2048 + k * 1024); } while (0)
; #define PG8_WAIT_V(n) asm volatile("s_waitcnt vmcnt(" #n ")" ::: "memory")
; #define PG8_WAIT_L(n) asm volatile("s_waitcnt lgkmcnt(" #n ")" ::: "memory")
; #define PG8_BAR __builtin_amdgcn_s_barrier()
; #define PG8_SCHED __builtin_amdgcn_sched_barrier(0)
; template <class Epi, class Sched, bool ALIGN_EPI = false, bool SP2 = false>
; __device__ __forceinline__ void gemm_phase(PG8_LAS unsigned char* lds, const Gemm g, const Sched& S, const Epi& E) {
;     ...
;         const bool has_next = S.next(ui + 1, nxt);
;         const char* nA = has_next ? (const char*)g.A + (size_t)nxt.pm * tstep : cA; const char* nB = has_next ? (const char*)g.Bt + (size_t)nxt.pn * tstep : cB;
;         for (int t = 0; t < nt; t += 2) {
;             const bool last = (t == nt - 2);
;             const char* a1 = cA + (size_t)(t + 1) * kstep;
;             const char* a2 = last ? nA : cA + (size_t)(t + 2) * kstep; const char* b2 = last ? nB : cB + (size_t)(t + 2) * kstep;
;             const char* a3 = a2 + kstep; const char* b3 = b2 + kstep;
;             if (last && has_next) S.a_ready(nxt);
;             if constexpr (SP2) {
;             PG8_LDB(B0, 0, 0); PG8_LDB(B1, 0, 1); PG8_SCHED; PG8_LDA(At, 0, 0); PG8_STAGE(PG8_SA(1, 1), a1 + hstep, voffA);
;             PG8_WAIT_V(8); PG8_WAIT_L(0); PG8_BAR; PG8_MMA(0, 0, At, B0); PG8_MMA(0, 1, At, B1); PG8_BAR; PG8_SCHED;
;             PG8_LDA(At, 0, 1); PG8_STAGE(PG8_SB(0, 0), b2, voffB); PG8_STAGE(PG8_SB(0, 1), b2 + hstep, voffB); PG8_STAGE(PG8_SA(0, 0), a2, voffA);
.LBB0_1065:
	s_add_u32 s37, s10, 0x100
	s_addc_u32 s38, s11, 0
	s_add_u32 s10, s6, 0x160080
	s_addc_u32 s11, s7, 0
	v_lshl_add_u64 v[140:141], s[10:11], 0, v[136:137]
	v_lshl_add_u64 v[142:143], s[10:11], 0, v[138:139]
	s_mov_b32 s39, -2
	s_mov_b64 s[10:11], 0
	.p2align 6
.LBB0_1066:
	s_add_u32 s12, s6, s10
	s_addc_u32 s13, s7, s11
	s_add_u32 s12, s12, 0x100
	s_addc_u32 s13, s13, 0
	s_add_u32 s40, s37, s10
	s_addc_u32 s41, s38, s11
	s_add_i32 s42, 0, 0x10000
	s_cmpk_eq_i32 s10, 0x2b00
	s_cselect_b32 s15, s9, s13
	s_cselect_b32 s14, s8, s12
	v_add_u32_e32 v160, s42, v144
	s_cselect_b32 s13, s5, s41
	s_cselect_b32 s12, s4, s40
	s_add_i32 s43, 0, 0x14000
	ds_read_b128 v[146:149], v160
	ds_read_b128 v[150:153], v160 offset:1024
	ds_read_b128 v[156:159], v160 offset:2048
	ds_read_b128 v[164:167], v160 offset:3072
	v_add_u32_e32 v160, s43, v144
	ds_read_b128 v[172:175], v160
	ds_read_b128 v[180:183], v160 offset:1024
	ds_read_b128 v[200:203], v160 offset:2048
	ds_read_b128 v[204:207], v160 offset:3072
	v_lshl_add_u64 v[160:161], v[140:141], 0, s[10:11]
	s_add_i32 m0, s26, 0xc000
	ds_read_b128 v[208:211], v145
	ds_read_b128 v[212:215], v145 offset:1024
	ds_read_b128 v[216:219], v145 offset:2048
	ds_read_b128 v[220:223], v145 offset:3072
	ds_read_b128 v[224:227], v145 offset:4096
	ds_read_b128 v[228:231], v145 offset:5120
	ds_read_b128 v[232:235], v145 offset:6144
	ds_read_b128 v[236:239], v145 offset:7168
	global_load_lds_dwordx4 v[160:161], off
	v_lshl_add_u64 v[160:161], v[142:143], 0, s[10:11]
	s_add_i32 m0, s26, 0xe000
	s_nop 0
	global_load_lds_dwordx4 v[160:161], off
	s_waitcnt vmcnt(8)
	s_waitcnt lgkmcnt(0)
	s_barrier
	s_setprio 1
	s_waitcnt lgkmcnt(0)
	v_mfma_f32_16x16x32_bf16 v[126:129], v[146:149], v[208:211], v[126:129]
	v_mfma_f32_16x16x32_bf16 v[122:125], v[156:159], v[208:211], v[122:125]
	v_mfma_f32_16x16x32_bf16 v[110:113], v[146:149], v[216:219], v[110:113]
	v_mfma_f32_16x16x32_bf16 v[106:109], v[156:159], v[216:219], v[106:109]
	v_mfma_f32_16x16x32_bf16 v[94:97], v[146:149], v[224:227], v[94:97]
	v_mfma_f32_16x16x32_bf16 v[90:93], v[156:159], v[224:227], v[90:93]
	v_mfma_f32_16x16x32_bf16 v[78:81], v[146:149], v[232:235], v[78:81]
	v_mfma_f32_16x16x32_bf16 v[74:77], v[156:159], v[232:235], v[74:77]
	v_mfma_f32_16x16x32_bf16 v[126:129], v[150:153], v[212:215], v[126:129]
	v_mfma_f32_16x16x32_bf16 v[122:125], v[164:167], v[212:215], v[122:125]
	v_mfma_f32_16x16x32_bf16 v[110:113], v[150:153], v[220:223], v[110:113]
	v_mfma_f32_16x16x32_bf16 v[106:109], v[164:167], v[220:223], v[106:109]
	v_mfma_f32_16x16x32_bf16 v[94:97], v[150:153], v[228:231], v[94:97]
	v_mfma_f32_16x16x32_bf16 v[90:93], v[164:167], v[228:231], v[90:93]
	v_mfma_f32_16x16x32_bf16 v[78:81], v[150:153], v[236:239], v[78:81]
	v_mfma_f32_16x16x32_bf16 v[74:77], v[164:167], v[236:239], v[74:77]
	v_mfma_f32_16x16x32_bf16 v[118:121], v[172:175], v[208:211], v[118:121]
	v_mfma_f32_16x16x32_bf16 v[114:117], v[200:203], v[208:211], v[114:117]
	v_mfma_f32_16x16x32_bf16 v[102:105], v[172:175], v[216:219], v[102:105]
	v_mfma_f32_16x16x32_bf16 v[98:101], v[200:203], v[216:219], v[98:101]
	v_mfma_f32_16x16x32_bf16 v[86:89], v[172:175], v[224:227], v[86:89]
	v_mfma_f32_16x16x32_bf16 v[82:85], v[200:203], v[224:227], v[82:85]
	v_mfma_f32_16x16x32_bf16 v[70:73], v[172:175], v[232:235], v[70:73]
	v_mfma_f32_16x16x32_bf16 v[66:69], v[200:203], v[232:235], v[66:69]
	v_mfma_f32_16x16x32_bf16 v[118:121], v[180:183], v[212:215], v[118:121]
	v_mfma_f32_16x16x32_bf16 v[114:117], v[204:207], v[212:215], v[114:117]
	v_mfma_f32_16x16x32_bf16 v[102:105], v[180:183], v[220:223], v[102:105]
	v_mfma_f32_16x16x32_bf16 v[98:101], v[204:207], v[220:223], v[98:101]
	v_mfma_f32_16x16x32_bf16 v[86:89], v[180:183], v[228:231], v[86:89]
	v_mfma_f32_16x16x32_bf16 v[82:85], v[204:207], v[228:231], v[82:85]
	v_mfma_f32_16x16x32_bf16 v[70:73], v[180:183], v[236:239], v[70:73]
	v_mfma_f32_16x16x32_bf16 v[66:69], v[204:207], v[236:239], v[66:69]
	s_setprio 0
	s_barrier
	s_add_i32 s40, s42, s25
	v_lshl_add_u64 v[160:161], s[12:13], 0, v[0:1]
	s_mov_b32 m0, s40
	ds_read_b128 v[208:211], v145 offset:16384
	ds_read_b128 v[212:215], v145 offset:17408
	ds_read_b128 v[216:219], v145 offset:18432
	ds_read_b128 v[220:223], v145 offset:19456
	ds_read_b128 v[224:227], v145 offset:20480
	ds_read_b128 v[228:231], v145 offset:21504
	ds_read_b128 v[232:235], v145 offset:22528
	ds_read_b128 v[236:239], v145 offset:23552
	global_load_lds_dwordx4 v[160:161], off
	s_add_i32 m0, s40, 0x2000
	s_add_u32 s40, s12, 0x160000
	v_lshl_add_u64 v[176:177], s[12:13], 0, v[130:131]
	s_addc_u32 s41, s13, 0
	s_add_i32 s42, s43, s25
	global_load_lds_dwordx4 v[176:177], off
	v_lshl_add_u64 v[184:185], s[40:41], 0, v[0:1]
	s_mov_b32 m0, s42
	v_lshl_add_u64 v[240:241], s[14:15], 0, v[132:133]
	global_load_lds_dwordx4 v[184:185], off
	v_lshl_add_u64 v[184:185], s[40:41], 0, v[130:131]
	s_add_i32 m0, s42, 0x2000
	s_nop 0
	global_load_lds_dwordx4 v[184:185], off
	v_lshl_add_u64 v[184:185], s[14:15], 0, v[134:135]
	s_mov_b32 m0, s26
	s_nop 0
	global_load_lds_dwordx4 v[184:185], off
	s_mov_b32 m0, s27
	s_nop 0
	global_load_lds_dwordx4 v[240:241], off
	s_waitcnt vmcnt(8)
	s_waitcnt lgkmcnt(0)
	s_barrier
; #define PG8_STAGE(bufoff, gbase, voff) do { _Pragma("unroll") for (int _i = 0; _i < 2; ++_i) \
;         __builtin_amdgcn_global_load_lds((const unsigned*)((const char*)(gbase) + (voff)[_i]), (PG8_LAS unsigned*)(lds + (bufoff) + ldsw + _i * 8192), 16, 0, 0); } while (0)
; #define PG8_LDA(dst, b, h) do { _Pragma("unroll") for (int m = 0; m < 4; ++m) _Pragma("unroll") for (int k = 0; k < 2; ++k) dst[m][k] = *(const PG8_LAS bf16x8*)(lds + PG8_SA(b, h) + aoff + m * 2048 + k * 1024); } while (0)
; #define PG8_LDB(dst, b, h) do { _Pragma("unroll") for (int n = 0; n < 2; ++n) _Pragma("unroll") for (int k = 0; k < 2; ++k) dst[n][k] = *(const PG8_LAS bf16x8*)(lds + PG8_SB(b, h) + boff + n * 2048 + k * 1024); } while (0)
; #define PG8_MMA(ai, bj, At, Bt) do { __builtin_amdgcn_s_setprio(1); _Pragma("unroll") for (int m = 0; m < 4; ++m) _Pragma("unroll") for (int n = 0; n < 2; ++n) _Pragma("unroll") for (int k = 0; k < 2; ++k) \
;         acc[ai][bj][m][n] = __builtin_amdgcn_mfma_f32_16x16x32_bf16(Bt[n][k], At[m][k], acc[ai][bj][m][n], 0, 0, 0); __builtin_amdgcn_s_setprio(0); } while (0)
; #define PG8_WAIT_V(n) asm volatile("s_waitcnt vmcnt(" #n ")" ::: "memory")
; #define PG8_WAIT_L(n) asm volatile("s_waitcnt lgkmcnt(" #n ")" ::: "memory")
; #define PG8_BAR __builtin_amdgcn_s_barrier()
; #define PG8_SCHED __builtin_amdgcn_sched_barrier(0)
; template <class Epi, class Sched, bool ALIGN_EPI = false, bool SP2 = false>
; __device__ __forceinline__ void gemm_phase(PG8_LAS unsigned char* lds, const Gemm g, const Sched& S, const Epi& E) {
;     ...
;             PG8_WAIT_V(8); PG8_WAIT_L(0); PG8_BAR; PG8_MMA(1, 0, At, B0); PG8_MMA(1, 1, At, B1); PG8_BAR; PG8_SCHED;
;             PG8_LDB(B0, 1, 0); PG8_LDB(B1, 1, 1); PG8_SCHED; PG8_LDA(At, 1, 0); PG8_STAGE(PG8_SA(0, 1), a2 + hstep, voffA);
;             PG8_WAIT_V(8); PG8_WAIT_L(0); PG8_BAR; PG8_MMA(0, 0, At, B0); PG8_MMA(0, 1, At, B1); PG8_BAR; PG8_SCHED;
	s_setprio 1
	s_waitcnt lgkmcnt(0)
	v_mfma_f32_16x16x32_bf16 v[62:65], v[146:149], v[208:211], v[62:65]
	v_mfma_f32_16x16x32_bf16 v[58:61], v[156:159], v[208:211], v[58:61]
	v_mfma_f32_16x16x32_bf16 v[46:49], v[146:149], v[216:219], v[46:49]
	v_mfma_f32_16x16x32_bf16 v[42:45], v[156:159], v[216:219], v[42:45]
	v_mfma_f32_16x16x32_bf16 v[30:33], v[146:149], v[224:227], v[30:33]
	v_mfma_f32_16x16x32_bf16 v[26:29], v[156:159], v[224:227], v[26:29]
	v_mfma_f32_16x16x32_bf16 v[14:17], v[146:149], v[232:235], v[14:17]
	v_mfma_f32_16x16x32_bf16 v[10:13], v[156:159], v[232:235], v[10:13]
	v_mfma_f32_16x16x32_bf16 v[62:65], v[150:153], v[212:215], v[62:65]
	v_mfma_f32_16x16x32_bf16 v[58:61], v[164:167], v[212:215], v[58:61]
	v_mfma_f32_16x16x32_bf16 v[46:49], v[150:153], v[220:223], v[46:49]
	v_mfma_f32_16x16x32_bf16 v[42:45], v[164:167], v[220:223], v[42:45]
	v_mfma_f32_16x16x32_bf16 v[30:33], v[150:153], v[228:231], v[30:33]
	v_mfma_f32_16x16x32_bf16 v[26:29], v[164:167], v[228:231], v[26:29]
	v_mfma_f32_16x16x32_bf16 v[14:17], v[150:153], v[236:239], v[14:17]
	v_mfma_f32_16x16x32_bf16 v[10:13], v[164:167], v[236:239], v[10:13]
	v_mfma_f32_16x16x32_bf16 v[54:57], v[172:175], v[208:211], v[54:57]
	v_mfma_f32_16x16x32_bf16 v[50:53], v[200:203], v[208:211], v[50:53]
	v_mfma_f32_16x16x32_bf16 v[38:41], v[172:175], v[216:219], v[38:41]
	v_mfma_f32_16x16x32_bf16 v[34:37], v[200:203], v[216:219], v[34:37]
	v_mfma_f32_16x16x32_bf16 v[22:25], v[172:175], v[224:227], v[22:25]
	v_mfma_f32_16x16x32_bf16 v[18:21], v[200:203], v[224:227], v[18:21]
	v_mfma_f32_16x16x32_bf16 v[6:9], v[172:175], v[232:235], v[6:9]
	v_mfma_f32_16x16x32_bf16 v[2:5], v[200:203], v[232:235], v[2:5]
	v_mfma_f32_16x16x32_bf16 v[54:57], v[180:183], v[212:215], v[54:57]
	v_mfma_f32_16x16x32_bf16 v[50:53], v[204:207], v[212:215], v[50:53]
	v_mfma_f32_16x16x32_bf16 v[38:41], v[180:183], v[220:223], v[38:41]
	v_mfma_f32_16x16x32_bf16 v[34:37], v[204:207], v[220:223], v[34:37]
	v_mfma_f32_16x16x32_bf16 v[22:25], v[180:183], v[228:231], v[22:25]
	v_mfma_f32_16x16x32_bf16 v[18:21], v[204:207], v[228:231], v[18:21]
	v_mfma_f32_16x16x32_bf16 v[6:9], v[180:183], v[236:239], v[6:9]
	v_mfma_f32_16x16x32_bf16 v[2:5], v[204:207], v[236:239], v[2:5]
	s_setprio 0
	s_barrier
	s_add_i32 s40, 0, 0x18000
	v_add_u32_e32 v162, s40, v144
	s_add_i32 s41, 0, 0x1c000
	ds_read_b128 v[146:149], v162
	ds_read_b128 v[150:153], v162 offset:1024
	ds_read_b128 v[156:159], v162 offset:2048
	ds_read_b128 v[164:167], v162 offset:3072
	v_add_u32_e32 v162, s41, v144
	ds_read_b128 v[172:175], v162
	ds_read_b128 v[180:183], v162 offset:1024
	ds_read_b128 v[200:203], v162 offset:2048
	ds_read_b128 v[204:207], v162 offset:3072
	s_add_u32 s14, s14, 0x160000
	s_addc_u32 s15, s15, 0
	s_mov_b32 m0, s28
	v_lshl_add_u64 v[242:243], s[14:15], 0, v[134:135]
	ds_read_b128 v[208:211], v145 offset:32768
	ds_read_b128 v[212:215], v145 offset:33792
	ds_read_b128 v[216:219], v145 offset:34816
	ds_read_b128 v[220:223], v145 offset:35840
	ds_read_b128 v[224:227], v145 offset:36864
	ds_read_b128 v[228:231], v145 offset:37888
	ds_read_b128 v[232:235], v145 offset:38912
	ds_read_b128 v[236:239], v145 offset:39936
	global_load_lds_dwordx4 v[242:243], off
	v_lshl_add_u64 v[242:243], s[14:15], 0, v[132:133]
	s_mov_b32 m0, s29
	s_nop 0
	global_load_lds_dwordx4 v[242:243], off
	s_waitcnt vmcnt(8)
	s_waitcnt lgkmcnt(0)
	s_barrier
	s_setprio 1
	s_waitcnt lgkmcnt(0)
	v_mfma_f32_16x16x32_bf16 v[126:129], v[146:149], v[208:211], v[126:129]
	v_mfma_f32_16x16x32_bf16 v[122:125], v[156:159], v[208:211], v[122:125]
	v_mfma_f32_16x16x32_bf16 v[110:113], v[146:149], v[216:219], v[110:113]
	v_mfma_f32_16x16x32_bf16 v[106:109], v[156:159], v[216:219], v[106:109]
	v_mfma_f32_16x16x32_bf16 v[94:97], v[146:149], v[224:227], v[94:97]
	v_mfma_f32_16x16x32_bf16 v[90:93], v[156:159], v[224:227], v[90:93]
	v_mfma_f32_16x16x32_bf16 v[78:81], v[146:149], v[232:235], v[78:81]
	v_mfma_f32_16x16x32_bf16 v[74:77], v[156:159], v[232:235], v[74:77]
	v_mfma_f32_16x16x32_bf16 v[126:129], v[150:153], v[212:215], v[126:129]
	v_mfma_f32_16x16x32_bf16 v[122:125], v[164:167], v[212:215], v[122:125]
	v_mfma_f32_16x16x32_bf16 v[110:113], v[150:153], v[220:223], v[110:113]
	v_mfma_f32_16x16x32_bf16 v[106:109], v[164:167], v[220:223], v[106:109]
	v_mfma_f32_16x16x32_bf16 v[94:97], v[150:153], v[228:231], v[94:97]
	v_mfma_f32_16x16x32_bf16 v[90:93], v[164:167], v[228:231], v[90:93]
	v_mfma_f32_16x16x32_bf16 v[78:81], v[150:153], v[236:239], v[78:81]
	v_mfma_f32_16x16x32_bf16 v[74:77], v[164:167], v[236:239], v[74:77]
	v_mfma_f32_16x16x32_bf16 v[118:121], v[172:175], v[208:211], v[118:121]
	v_mfma_f32_16x16x32_bf16 v[114:117], v[200:203], v[208:211], v[114:117]
	v_mfma_f32_16x16x32_bf16 v[102:105], v[172:175], v[216:219], v[102:105]
	v_mfma_f32_16x16x32_bf16 v[98:101], v[200:203], v[216:219], v[98:101]
	v_mfma_f32_16x16x32_bf16 v[86:89], v[172:175], v[224:227], v[86:89]
	v_mfma_f32_16x16x32_bf16 v[82:85], v[200:203], v[224:227], v[82:85]
	v_mfma_f32_16x16x32_bf16 v[70:73], v[172:175], v[232:235], v[70:73]
	v_mfma_f32_16x16x32_bf16 v[66:69], v[200:203], v[232:235], v[66:69]
	v_mfma_f32_16x16x32_bf16 v[118:121], v[180:183], v[212:215], v[118:121]
	v_mfma_f32_16x16x32_bf16 v[114:117], v[204:207], v[212:215], v[114:117]
	v_mfma_f32_16x16x32_bf16 v[102:105], v[180:183], v[220:223], v[102:105]
	v_mfma_f32_16x16x32_bf16 v[98:101], v[204:207], v[220:223], v[98:101]
	v_mfma_f32_16x16x32_bf16 v[86:89], v[180:183], v[228:231], v[86:89]
	v_mfma_f32_16x16x32_bf16 v[82:85], v[204:207], v[228:231], v[82:85]
	v_mfma_f32_16x16x32_bf16 v[70:73], v[180:183], v[236:239], v[70:73]
	v_mfma_f32_16x16x32_bf16 v[66:69], v[204:207], v[236:239], v[66:69]
	s_setprio 0
	s_barrier
; #define PG8_STAGE(bufoff, gbase, voff) do { _Pragma("unroll") for (int _i = 0; _i < 2; ++_i) \
;         __builtin_amdgcn_global_load_lds((const unsigned*)((const char*)(gbase) + (voff)[_i]), (PG8_LAS unsigned*)(lds + (bufoff) + ldsw + _i * 8192), 16, 0, 0); } while (0)
; #define PG8_LDA(dst, b, h) do { _Pragma("unroll") for (int m = 0; m < 4; ++m) _Pragma("unroll") for (int k = 0; k < 2; ++k) dst[m][k] = *(const PG8_LAS bf16x8*)(lds + PG8_SA(b, h) + aoff + m * 2048 + k * 1024); } while (0)
; #define PG8_MMA(ai, bj, At, Bt) do { __builtin_amdgcn_s_setprio(1); _Pragma("unroll") for (int m = 0; m < 4; ++m) _Pragma("unroll") for (int n = 0; n < 2; ++n) _Pragma("unroll") for (int k = 0; k < 2; ++k) \
;         acc[ai][bj][m][n] = __builtin_amdgcn_mfma_f32_16x16x32_bf16(Bt[n][k], At[m][k], acc[ai][bj][m][n], 0, 0, 0); __builtin_amdgcn_s_setprio(0); } while (0)
; #define PG8_WAIT_V(n) asm volatile("s_waitcnt vmcnt(" #n ")" ::: "memory")
; #define PG8_WAIT_L(n) asm volatile("s_waitcnt lgkmcnt(" #n ")" ::: "memory")
; #define PG8_BAR __builtin_amdgcn_s_barrier()
; #define PG8_SCHED __builtin_amdgcn_sched_barrier(0)
; template <class Epi, class Sched, bool ALIGN_EPI = false, bool SP2 = false>
; __device__ __forceinline__ void gemm_phase(PG8_LAS unsigned char* lds, const Gemm g, const Sched& S, const Epi& E) {
;     ...
;             PG8_LDA(At, 1, 1); PG8_STAGE(PG8_SB(1, 0), b3, voffB); PG8_STAGE(PG8_SB(1, 1), b3 + hstep, voffB); PG8_STAGE(PG8_SA(1, 0), a3, voffA);
;             PG8_WAIT_V(8); PG8_WAIT_L(0); PG8_BAR; PG8_MMA(1, 0, At, B0); PG8_MMA(1, 1, At, B1); PG8_BAR; PG8_SCHED;
;     ...
;         if (!has_next) break;
; #pragma unroll
;         for (int a = 0; a < 2; ++a)
; #pragma unroll
;             for (int b = 0; b < 2; ++b)
; #pragma unroll
;                 for (int m = 0; m < 4; ++m)
; #pragma unroll
;                     for (int n = 0; n < 2; ++n) acc[a][b][m][n] = (f32x4){0.f, 0.f, 0.f, 0.f};
;         cur = nxt; cA = nA; cB = nB; ++ui;
	s_add_i32 s14, s40, s25
	v_lshl_add_u64 v[160:161], v[160:161], 0, s[44:45]
	s_mov_b32 m0, s14
	ds_read_b128 v[208:211], v145 offset:49152
	ds_read_b128 v[212:215], v145 offset:50176
	ds_read_b128 v[216:219], v145 offset:51200
	ds_read_b128 v[220:223], v145 offset:52224
	ds_read_b128 v[224:227], v145 offset:53248
	ds_read_b128 v[228:231], v145 offset:54272
	ds_read_b128 v[232:235], v145 offset:55296
	ds_read_b128 v[236:239], v145 offset:56320
	global_load_lds_dwordx4 v[160:161], off
	s_add_i32 m0, s14, 0x2000
	s_add_u32 s12, s12, 0x160080
	v_lshl_add_u64 v[160:161], v[176:177], 0, s[44:45]
	s_addc_u32 s13, s13, 0
	s_add_i32 s14, s41, s25
	global_load_lds_dwordx4 v[160:161], off
	v_lshl_add_u64 v[160:161], s[12:13], 0, v[0:1]
	s_mov_b32 m0, s14
	s_nop 0
	global_load_lds_dwordx4 v[160:161], off
	v_lshl_add_u64 v[160:161], s[12:13], 0, v[130:131]
	s_add_i32 m0, s14, 0x2000
	s_nop 0
	global_load_lds_dwordx4 v[160:161], off
	v_lshl_add_u64 v[160:161], v[184:185], 0, s[44:45]
	s_mov_b32 m0, s30
	s_nop 0
	global_load_lds_dwordx4 v[160:161], off
	v_lshl_add_u64 v[160:161], v[240:241], 0, s[44:45]
	s_mov_b32 m0, s31
	s_nop 0
	global_load_lds_dwordx4 v[160:161], off
	s_waitcnt vmcnt(8)
	s_waitcnt lgkmcnt(0)
	s_barrier
	s_setprio 1
	s_waitcnt lgkmcnt(0)
	v_mfma_f32_16x16x32_bf16 v[62:65], v[146:149], v[208:211], v[62:65]
	v_mfma_f32_16x16x32_bf16 v[58:61], v[156:159], v[208:211], v[58:61]
	v_mfma_f32_16x16x32_bf16 v[46:49], v[146:149], v[216:219], v[46:49]
	v_mfma_f32_16x16x32_bf16 v[42:45], v[156:159], v[216:219], v[42:45]
	v_mfma_f32_16x16x32_bf16 v[30:33], v[146:149], v[224:227], v[30:33]
	v_mfma_f32_16x16x32_bf16 v[26:29], v[156:159], v[224:227], v[26:29]
	v_mfma_f32_16x16x32_bf16 v[14:17], v[146:149], v[232:235], v[14:17]
	v_mfma_f32_16x16x32_bf16 v[10:13], v[156:159], v[232:235], v[10:13]
	v_mfma_f32_16x16x32_bf16 v[62:65], v[150:153], v[212:215], v[62:65]
	v_mfma_f32_16x16x32_bf16 v[58:61], v[164:167], v[212:215], v[58:61]
	v_mfma_f32_16x16x32_bf16 v[46:49], v[150:153], v[220:223], v[46:49]
	v_mfma_f32_16x16x32_bf16 v[42:45], v[164:167], v[220:223], v[42:45]
	v_mfma_f32_16x16x32_bf16 v[30:33], v[150:153], v[228:231], v[30:33]
	v_mfma_f32_16x16x32_bf16 v[26:29], v[164:167], v[228:231], v[26:29]
	v_mfma_f32_16x16x32_bf16 v[14:17], v[150:153], v[236:239], v[14:17]
	v_mfma_f32_16x16x32_bf16 v[10:13], v[164:167], v[236:239], v[10:13]
	v_mfma_f32_16x16x32_bf16 v[54:57], v[172:175], v[208:211], v[54:57]
	v_mfma_f32_16x16x32_bf16 v[50:53], v[200:203], v[208:211], v[50:53]
	v_mfma_f32_16x16x32_bf16 v[38:41], v[172:175], v[216:219], v[38:41]
	v_mfma_f32_16x16x32_bf16 v[34:37], v[200:203], v[216:219], v[34:37]
	v_mfma_f32_16x16x32_bf16 v[22:25], v[172:175], v[224:227], v[22:25]
	v_mfma_f32_16x16x32_bf16 v[18:21], v[200:203], v[224:227], v[18:21]
	v_mfma_f32_16x16x32_bf16 v[6:9], v[172:175], v[232:235], v[6:9]
	v_mfma_f32_16x16x32_bf16 v[2:5], v[200:203], v[232:235], v[2:5]
	v_mfma_f32_16x16x32_bf16 v[54:57], v[180:183], v[212:215], v[54:57]
	v_mfma_f32_16x16x32_bf16 v[50:53], v[204:207], v[212:215], v[50:53]
	v_mfma_f32_16x16x32_bf16 v[38:41], v[180:183], v[220:223], v[38:41]
	v_mfma_f32_16x16x32_bf16 v[34:37], v[204:207], v[220:223], v[34:37]
	v_mfma_f32_16x16x32_bf16 v[22:25], v[180:183], v[228:231], v[22:25]
	v_mfma_f32_16x16x32_bf16 v[18:21], v[204:207], v[228:231], v[18:21]
	v_mfma_f32_16x16x32_bf16 v[6:9], v[180:183], v[236:239], v[6:9]
	v_mfma_f32_16x16x32_bf16 v[2:5], v[204:207], v[236:239], v[2:5]
	s_setprio 0
	s_barrier
	s_add_i32 s39, s39, 2
	s_add_u32 s10, s10, 0x100
	s_addc_u32 s11, s11, 0
	s_cmpk_gt_u32 s39, 0x55
	s_cbranch_scc0 .LBB0_1066
	s_add_u32 s10, s37, 0xffffff00
	s_addc_u32 s11, s38, -1
	s_and_b64 vcc, exec, s[2:3]
	s_cbranch_vccnz .LBB0_1053
	v_mov_b32_e32 v2, 0
	s_mov_b32 s21, s34
	s_mov_b32 s20, s35
	s_mov_b64 s[6:7], s[8:9]
	s_mov_b32 s33, s36
	v_mov_b32_e32 v3, v2
	v_mov_b32_e32 v4, v2
	v_mov_b32_e32 v5, v2
	v_mov_b32_e32 v6, v2
	v_mov_b32_e32 v7, v2
	v_mov_b32_e32 v8, v2
	v_mov_b32_e32 v9, v2
	v_mov_b32_e32 v18, v2
	v_mov_b32_e32 v19, v2
	v_mov_b32_e32 v20, v2
	v_mov_b32_e32 v21, v2
	v_mov_b32_e32 v22, v2
	v_mov_b32_e32 v23, v2
	v_mov_b32_e32 v24, v2
	v_mov_b32_e32 v25, v2
	v_mov_b32_e32 v34, v2
	v_mov_b32_e32 v35, v2
	v_mov_b32_e32 v36, v2
	v_mov_b32_e32 v37, v2
	v_mov_b32_e32 v38, v2
	v_mov_b32_e32 v39, v2
	v_mov_b32_e32 v40, v2
	v_mov_b32_e32 v41, v2
	v_mov_b32_e32 v50, v2
	v_mov_b32_e32 v51, v2
	v_mov_b32_e32 v52, v2
	v_mov_b32_e32 v53, v2
	v_mov_b32_e32 v54, v2
	v_mov_b32_e32 v55, v2
	v_mov_b32_e32 v56, v2
	v_mov_b32_e32 v57, v2
	v_mov_b32_e32 v10, v2
	v_mov_b32_e32 v11, v2
	v_mov_b32_e32 v12, v2
	v_mov_b32_e32 v13, v2
	v_mov_b32_e32 v14, v2
	v_mov_b32_e32 v15, v2
	v_mov_b32_e32 v16, v2
	v_mov_b32_e32 v17, v2
	v_mov_b32_e32 v26, v2
	v_mov_b32_e32 v27, v2
	v_mov_b32_e32 v28, v2
	v_mov_b32_e32 v29, v2
	v_mov_b32_e32 v30, v2
	v_mov_b32_e32 v31, v2
	v_mov_b32_e32 v32, v2
	v_mov_b32_e32 v33, v2
	v_mov_b32_e32 v42, v2
	v_mov_b32_e32 v43, v2
	v_mov_b32_e32 v44, v2
	v_mov_b32_e32 v45, v2
	v_mov_b32_e32 v46, v2
	v_mov_b32_e32 v47, v2
	v_mov_b32_e32 v48, v2
	v_mov_b32_e32 v49, v2
	v_mov_b32_e32 v58, v2
	v_mov_b32_e32 v59, v2
	v_mov_b32_e32 v60, v2
	v_mov_b32_e32 v61, v2
	v_mov_b32_e32 v62, v2
	v_mov_b32_e32 v63, v2
	v_mov_b32_e32 v64, v2
	v_mov_b32_e32 v65, v2
	v_mov_b32_e32 v66, v2
	v_mov_b32_e32 v67, v2
	v_mov_b32_e32 v68, v2
	v_mov_b32_e32 v69, v2
	v_mov_b32_e32 v70, v2
	v_mov_b32_e32 v71, v2
	v_mov_b32_e32 v72, v2
	v_mov_b32_e32 v73, v2
	v_mov_b32_e32 v82, v2
	v_mov_b32_e32 v83, v2
	v_mov_b32_e32 v84, v2
	v_mov_b32_e32 v85, v2
	v_mov_b32_e32 v86, v2
	v_mov_b32_e32 v87, v2
	v_mov_b32_e32 v88, v2
	v_mov_b32_e32 v89, v2
	v_mov_b32_e32 v98, v2
	v_mov_b32_e32 v99, v2
	v_mov_b32_e32 v100, v2
	v_mov_b32_e32 v101, v2
	v_mov_b32_e32 v102, v2
	v_mov_b32_e32 v103, v2
	v_mov_b32_e32 v104, v2
	v_mov_b32_e32 v105, v2
	v_mov_b32_e32 v114, v2
	v_mov_b32_e32 v115, v2
	v_mov_b32_e32 v116, v2
	v_mov_b32_e32 v117, v2
	v_mov_b32_e32 v118, v2
	v_mov_b32_e32 v119, v2
	v_mov_b32_e32 v120, v2
	v_mov_b32_e32 v121, v2
	v_mov_b32_e32 v74, v2
	v_mov_b32_e32 v75, v2
	v_mov_b32_e32 v76, v2
	v_mov_b32_e32 v77, v2
	v_mov_b32_e32 v78, v2
	v_mov_b32_e32 v79, v2
	v_mov_b32_e32 v80, v2
	v_mov_b32_e32 v81, v2
	v_mov_b32_e32 v90, v2
	v_mov_b32_e32 v91, v2
	v_mov_b32_e32 v92, v2
	v_mov_b32_e32 v93, v2
	v_mov_b32_e32 v94, v2
	v_mov_b32_e32 v95, v2
	v_mov_b32_e32 v96, v2
	v_mov_b32_e32 v97, v2
	v_mov_b32_e32 v106, v2
	v_mov_b32_e32 v107, v2
	v_mov_b32_e32 v108, v2
	v_mov_b32_e32 v109, v2
	v_mov_b32_e32 v110, v2
	v_mov_b32_e32 v111, v2
	v_mov_b32_e32 v112, v2
	v_mov_b32_e32 v113, v2
	v_mov_b32_e32 v122, v2
	v_mov_b32_e32 v123, v2
	v_mov_b32_e32 v124, v2
	v_mov_b32_e32 v125, v2
	v_mov_b32_e32 v126, v2
	v_mov_b32_e32 v127, v2
	v_mov_b32_e32 v128, v2
	v_mov_b32_e32 v129, v2
	s_andn2_b64 vcc, exec, s[0:1]
	s_cbranch_vccnz .LBB0_1054
